# GEMM K-loops: per-segment setprio flips removed, one static s_setprio 1 for the trailing half around each unit's K-loop (all six GEMM phases); on top of v2
# speedup vs baseline: 1.0163x; 1.0081x over previous
.LBB0_212:
	s_ashr_i32 s47, s46, 31
	s_lshl_b64 s[8:9], s[46:47], 20
	s_add_u32 s48, s30, s8
	s_addc_u32 s49, s31, s9
	s_and_b64 s[8:9], s[2:3], exec
	s_cselect_b32 s8, s49, s85
	s_cselect_b32 s9, s48, s84
	s_ashr_i32 s45, s44, 31
	s_lshl_b64 s[12:13], s[44:45], 20
	s_add_u32 s50, s14, s12
	s_addc_u32 s51, s15, s13
	s_and_b64 s[12:13], s[2:3], exec
	s_cselect_b32 s12, s51, s87
	s_cselect_b32 s13, s50, s86
	s_add_u32 s84, s84, 0x80080
	s_addc_u32 s85, s85, 0
	s_add_u32 s16, s86, 0x100
	v_mov_b32_e32 v2, 0
	s_addc_u32 s17, s87, 0
	s_mov_b32 s18, -2
	v_mov_b32_e32 v3, v2
	v_mov_b32_e32 v4, v2
	v_mov_b32_e32 v5, v2
	v_mov_b32_e32 v6, v2
	v_mov_b32_e32 v7, v2
	v_mov_b32_e32 v8, v2
	v_mov_b32_e32 v9, v2
	v_mov_b32_e32 v18, v2
	v_mov_b32_e32 v19, v2
	v_mov_b32_e32 v20, v2
	v_mov_b32_e32 v21, v2
	v_mov_b32_e32 v22, v2
	v_mov_b32_e32 v23, v2
	v_mov_b32_e32 v24, v2
	v_mov_b32_e32 v25, v2
	v_mov_b32_e32 v34, v2
	v_mov_b32_e32 v35, v2
	v_mov_b32_e32 v36, v2
	v_mov_b32_e32 v37, v2
	v_mov_b32_e32 v38, v2
	v_mov_b32_e32 v39, v2
	v_mov_b32_e32 v40, v2
	v_mov_b32_e32 v41, v2
	v_mov_b32_e32 v50, v2
	v_mov_b32_e32 v51, v2
	v_mov_b32_e32 v52, v2
	v_mov_b32_e32 v53, v2
	v_mov_b32_e32 v54, v2
	v_mov_b32_e32 v55, v2
	v_mov_b32_e32 v56, v2
	v_mov_b32_e32 v57, v2
	v_mov_b32_e32 v10, v2
	v_mov_b32_e32 v11, v2
	v_mov_b32_e32 v12, v2
	v_mov_b32_e32 v13, v2
	v_mov_b32_e32 v14, v2
	v_mov_b32_e32 v15, v2
	v_mov_b32_e32 v16, v2
	v_mov_b32_e32 v17, v2
	v_mov_b32_e32 v26, v2
	v_mov_b32_e32 v27, v2
	v_mov_b32_e32 v28, v2
	v_mov_b32_e32 v29, v2
	v_mov_b32_e32 v30, v2
	v_mov_b32_e32 v31, v2
	v_mov_b32_e32 v32, v2
	v_mov_b32_e32 v33, v2
	v_mov_b32_e32 v42, v2
	v_mov_b32_e32 v43, v2
	v_mov_b32_e32 v44, v2
	v_mov_b32_e32 v45, v2
	v_mov_b32_e32 v46, v2
	v_mov_b32_e32 v47, v2
	v_mov_b32_e32 v48, v2
	v_mov_b32_e32 v49, v2
	v_mov_b32_e32 v58, v2
	v_mov_b32_e32 v59, v2
	v_mov_b32_e32 v60, v2
	v_mov_b32_e32 v61, v2
	v_mov_b32_e32 v62, v2
	v_mov_b32_e32 v63, v2
	v_mov_b32_e32 v64, v2
	v_mov_b32_e32 v65, v2
	v_mov_b32_e32 v66, v2
	v_mov_b32_e32 v67, v2
	v_mov_b32_e32 v68, v2
	v_mov_b32_e32 v69, v2
	v_mov_b32_e32 v70, v2
	v_mov_b32_e32 v71, v2
	v_mov_b32_e32 v72, v2
	v_mov_b32_e32 v73, v2
	v_mov_b32_e32 v82, v2
	v_mov_b32_e32 v83, v2
	v_mov_b32_e32 v84, v2
	v_mov_b32_e32 v85, v2
	v_mov_b32_e32 v86, v2
	v_mov_b32_e32 v87, v2
	v_mov_b32_e32 v88, v2
	v_mov_b32_e32 v89, v2
	v_mov_b32_e32 v98, v2
	v_mov_b32_e32 v99, v2
	v_mov_b32_e32 v100, v2
	v_mov_b32_e32 v101, v2
	v_mov_b32_e32 v102, v2
	v_mov_b32_e32 v103, v2
	v_mov_b32_e32 v104, v2
	v_mov_b32_e32 v105, v2
	v_mov_b32_e32 v114, v2
	v_mov_b32_e32 v115, v2
	v_mov_b32_e32 v116, v2
	v_mov_b32_e32 v117, v2
	v_mov_b32_e32 v118, v2
	v_mov_b32_e32 v119, v2
	v_mov_b32_e32 v120, v2
	v_mov_b32_e32 v121, v2
	v_mov_b32_e32 v74, v2
	v_mov_b32_e32 v75, v2
	v_mov_b32_e32 v76, v2
	v_mov_b32_e32 v77, v2
	v_mov_b32_e32 v78, v2
	v_mov_b32_e32 v79, v2
	v_mov_b32_e32 v80, v2
	v_mov_b32_e32 v81, v2
	v_mov_b32_e32 v90, v2
	v_mov_b32_e32 v91, v2
	v_mov_b32_e32 v92, v2
	v_mov_b32_e32 v93, v2
	v_mov_b32_e32 v94, v2
	v_mov_b32_e32 v95, v2
	v_mov_b32_e32 v96, v2
	v_mov_b32_e32 v97, v2
	v_mov_b32_e32 v106, v2
	v_mov_b32_e32 v107, v2
	v_mov_b32_e32 v108, v2
	v_mov_b32_e32 v109, v2
	v_mov_b32_e32 v110, v2
	v_mov_b32_e32 v111, v2
	v_mov_b32_e32 v112, v2
	v_mov_b32_e32 v113, v2
	v_mov_b32_e32 v122, v2
	v_mov_b32_e32 v123, v2
	v_mov_b32_e32 v124, v2
	v_mov_b32_e32 v125, v2
	v_mov_b32_e32 v126, v2
	v_mov_b32_e32 v127, v2
	v_mov_b32_e32 v128, v2
	v_mov_b32_e32 v129, v2
	s_and_b64 vcc, exec, s[6:7]
	s_cbranch_vccnz .Lsp_p2
	s_setprio 1
.Lsp_p2:
.LBB0_213:
	ds_read_b128 v[146:149], v156
	ds_read_b128 v[150:153], v156 offset:1024
	ds_read_b128 v[160:163], v156 offset:2048
	ds_read_b128 v[164:167], v156 offset:3072
	ds_read_b128 v[168:171], v157
	ds_read_b128 v[172:175], v157 offset:1024
	ds_read_b128 v[176:179], v157 offset:2048
	ds_read_b128 v[180:183], v157 offset:3072
	s_add_u32 s19, s84, 0xfff80080
	s_addc_u32 s20, s85, -1
	s_cmp_eq_u32 s18, 28
	s_cselect_b32 s89, s8, s20
	s_cselect_b32 s88, s9, s19
	s_cselect_b32 s87, s12, s17
	s_cselect_b32 s86, s13, s16
	v_lshl_add_u64 v[216:217], s[84:85], 0, v[138:139]
	s_add_i32 m0, s57, 0xc000
	ds_read_b128 v[184:187], v158
	ds_read_b128 v[188:191], v158 offset:1024
	ds_read_b128 v[192:195], v158 offset:2048
	ds_read_b128 v[196:199], v158 offset:3072
	ds_read_b128 v[200:203], v158 offset:4096
	ds_read_b128 v[204:207], v158 offset:5120
	ds_read_b128 v[208:211], v158 offset:6144
	ds_read_b128 v[212:215], v158 offset:7168
	global_load_lds_dwordx4 v[216:217], off
	v_lshl_add_u64 v[216:217], s[84:85], 0, v[140:141]
	s_add_i32 m0, s57, 0xe000
	s_nop 0
	global_load_lds_dwordx4 v[216:217], off
	s_waitcnt vmcnt(8)
	s_waitcnt lgkmcnt(0)
	s_barrier
	s_waitcnt lgkmcnt(0)
	v_mfma_i32_16x16x64_i8 v[126:129], v[146:149], v[184:187], v[126:129]
	v_mfma_i32_16x16x64_i8 v[122:125], v[160:163], v[184:187], v[122:125]
	v_mfma_i32_16x16x64_i8 v[110:113], v[146:149], v[192:195], v[110:113]
	v_mfma_i32_16x16x64_i8 v[106:109], v[160:163], v[192:195], v[106:109]
	v_mfma_i32_16x16x64_i8 v[94:97], v[146:149], v[200:203], v[94:97]
	v_mfma_i32_16x16x64_i8 v[90:93], v[160:163], v[200:203], v[90:93]
	v_mfma_i32_16x16x64_i8 v[78:81], v[146:149], v[208:211], v[78:81]
	v_mfma_i32_16x16x64_i8 v[74:77], v[160:163], v[208:211], v[74:77]
	v_mfma_i32_16x16x64_i8 v[126:129], v[150:153], v[188:191], v[126:129]
	v_mfma_i32_16x16x64_i8 v[122:125], v[164:167], v[188:191], v[122:125]
	v_mfma_i32_16x16x64_i8 v[110:113], v[150:153], v[196:199], v[110:113]
	v_mfma_i32_16x16x64_i8 v[106:109], v[164:167], v[196:199], v[106:109]
	v_mfma_i32_16x16x64_i8 v[94:97], v[150:153], v[204:207], v[94:97]
	v_mfma_i32_16x16x64_i8 v[90:93], v[164:167], v[204:207], v[90:93]
	v_mfma_i32_16x16x64_i8 v[78:81], v[150:153], v[212:215], v[78:81]
	v_mfma_i32_16x16x64_i8 v[74:77], v[164:167], v[212:215], v[74:77]
	v_mfma_i32_16x16x64_i8 v[118:121], v[168:171], v[184:187], v[118:121]
	v_mfma_i32_16x16x64_i8 v[114:117], v[176:179], v[184:187], v[114:117]
	v_mfma_i32_16x16x64_i8 v[102:105], v[168:171], v[192:195], v[102:105]
	v_mfma_i32_16x16x64_i8 v[98:101], v[176:179], v[192:195], v[98:101]
	v_mfma_i32_16x16x64_i8 v[86:89], v[168:171], v[200:203], v[86:89]
	v_mfma_i32_16x16x64_i8 v[82:85], v[176:179], v[200:203], v[82:85]
	v_mfma_i32_16x16x64_i8 v[70:73], v[168:171], v[208:211], v[70:73]
	v_mfma_i32_16x16x64_i8 v[66:69], v[176:179], v[208:211], v[66:69]
	v_mfma_i32_16x16x64_i8 v[118:121], v[172:175], v[188:191], v[118:121]
	v_mfma_i32_16x16x64_i8 v[114:117], v[180:183], v[188:191], v[114:117]
	v_mfma_i32_16x16x64_i8 v[102:105], v[172:175], v[196:199], v[102:105]
	v_mfma_i32_16x16x64_i8 v[98:101], v[180:183], v[196:199], v[98:101]
	v_mfma_i32_16x16x64_i8 v[86:89], v[172:175], v[204:207], v[86:89]
	v_mfma_i32_16x16x64_i8 v[82:85], v[180:183], v[204:207], v[82:85]
	v_mfma_i32_16x16x64_i8 v[70:73], v[172:175], v[212:215], v[70:73]
	v_mfma_i32_16x16x64_i8 v[66:69], v[180:183], v[212:215], v[66:69]
	s_barrier
	s_add_i32 s19, s83, s35
	v_lshl_add_u64 v[216:217], s[86:87], 0, v[134:135]
	s_mov_b32 m0, s19
	ds_read_b128 v[184:187], v158 offset:16384
	ds_read_b128 v[188:191], v158 offset:17408
	ds_read_b128 v[192:195], v158 offset:18432
	ds_read_b128 v[196:199], v158 offset:19456
	ds_read_b128 v[200:203], v158 offset:20480
	ds_read_b128 v[204:207], v158 offset:21504
	ds_read_b128 v[208:211], v158 offset:22528
	ds_read_b128 v[212:215], v158 offset:23552
	global_load_lds_dwordx4 v[216:217], off
	s_add_i32 m0, s19, 0x2000
	s_add_u32 s20, s86, 0x80000
	v_lshl_add_u64 v[218:219], s[86:87], 0, v[130:131]
	s_addc_u32 s21, s87, 0
	s_add_i32 s19, s90, s35
	global_load_lds_dwordx4 v[218:219], off
	v_lshl_add_u64 v[220:221], s[20:21], 0, v[134:135]
	s_mov_b32 m0, s19
	v_lshl_add_u64 v[222:223], s[88:89], 0, v[132:133]
	global_load_lds_dwordx4 v[220:221], off
	v_lshl_add_u64 v[220:221], s[20:21], 0, v[130:131]
	s_add_i32 m0, s19, 0x2000
	s_nop 0
	global_load_lds_dwordx4 v[220:221], off
	v_lshl_add_u64 v[220:221], s[88:89], 0, v[136:137]
	s_mov_b32 m0, s57
	s_nop 0
	global_load_lds_dwordx4 v[220:221], off
	s_mov_b32 m0, s58
	s_nop 0
	global_load_lds_dwordx4 v[222:223], off
	s_waitcnt vmcnt(8)
	s_waitcnt lgkmcnt(0)
	s_barrier
	s_waitcnt lgkmcnt(0)
	v_mfma_i32_16x16x64_i8 v[62:65], v[146:149], v[184:187], v[62:65]
	v_mfma_i32_16x16x64_i8 v[58:61], v[160:163], v[184:187], v[58:61]
	v_mfma_i32_16x16x64_i8 v[46:49], v[146:149], v[192:195], v[46:49]
	v_mfma_i32_16x16x64_i8 v[42:45], v[160:163], v[192:195], v[42:45]
	v_mfma_i32_16x16x64_i8 v[30:33], v[146:149], v[200:203], v[30:33]
	v_mfma_i32_16x16x64_i8 v[26:29], v[160:163], v[200:203], v[26:29]
	v_mfma_i32_16x16x64_i8 v[14:17], v[146:149], v[208:211], v[14:17]
	v_mfma_i32_16x16x64_i8 v[10:13], v[160:163], v[208:211], v[10:13]
	v_mfma_i32_16x16x64_i8 v[62:65], v[150:153], v[188:191], v[62:65]
	v_mfma_i32_16x16x64_i8 v[58:61], v[164:167], v[188:191], v[58:61]
	v_mfma_i32_16x16x64_i8 v[46:49], v[150:153], v[196:199], v[46:49]
	v_mfma_i32_16x16x64_i8 v[42:45], v[164:167], v[196:199], v[42:45]
	v_mfma_i32_16x16x64_i8 v[30:33], v[150:153], v[204:207], v[30:33]
	v_mfma_i32_16x16x64_i8 v[26:29], v[164:167], v[204:207], v[26:29]
	v_mfma_i32_16x16x64_i8 v[14:17], v[150:153], v[212:215], v[14:17]
	v_mfma_i32_16x16x64_i8 v[10:13], v[164:167], v[212:215], v[10:13]
	v_mfma_i32_16x16x64_i8 v[54:57], v[168:171], v[184:187], v[54:57]
	v_mfma_i32_16x16x64_i8 v[50:53], v[176:179], v[184:187], v[50:53]
	v_mfma_i32_16x16x64_i8 v[38:41], v[168:171], v[192:195], v[38:41]
	v_mfma_i32_16x16x64_i8 v[34:37], v[176:179], v[192:195], v[34:37]
	v_mfma_i32_16x16x64_i8 v[22:25], v[168:171], v[200:203], v[22:25]
	v_mfma_i32_16x16x64_i8 v[18:21], v[176:179], v[200:203], v[18:21]
	v_mfma_i32_16x16x64_i8 v[6:9], v[168:171], v[208:211], v[6:9]
	v_mfma_i32_16x16x64_i8 v[2:5], v[176:179], v[208:211], v[2:5]
	v_mfma_i32_16x16x64_i8 v[54:57], v[172:175], v[188:191], v[54:57]
	v_mfma_i32_16x16x64_i8 v[50:53], v[180:183], v[188:191], v[50:53]
	v_mfma_i32_16x16x64_i8 v[38:41], v[172:175], v[196:199], v[38:41]
	v_mfma_i32_16x16x64_i8 v[34:37], v[180:183], v[196:199], v[34:37]
	v_mfma_i32_16x16x64_i8 v[22:25], v[172:175], v[204:207], v[22:25]
	v_mfma_i32_16x16x64_i8 v[18:21], v[180:183], v[204:207], v[18:21]
	v_mfma_i32_16x16x64_i8 v[6:9], v[172:175], v[212:215], v[6:9]
	v_mfma_i32_16x16x64_i8 v[2:5], v[180:183], v[212:215], v[2:5]
	s_barrier
	s_add_i32 s19, 0, 0x18000
	v_add_u32_e32 v159, s19, v154
	s_add_i32 s22, 0, 0x1c000
	ds_read_b128 v[146:149], v159
	ds_read_b128 v[150:153], v159 offset:1024
	ds_read_b128 v[160:163], v159 offset:2048
	ds_read_b128 v[164:167], v159 offset:3072
	v_add_u32_e32 v159, s22, v154
	ds_read_b128 v[168:171], v159
	ds_read_b128 v[172:175], v159 offset:1024
	ds_read_b128 v[176:179], v159 offset:2048
	ds_read_b128 v[180:183], v159 offset:3072
	s_add_u32 s20, s88, 0x80000
	s_addc_u32 s21, s89, 0
	s_mov_b32 m0, s59
	v_lshl_add_u64 v[224:225], s[20:21], 0, v[136:137]
	ds_read_b128 v[184:187], v158 offset:32768
	ds_read_b128 v[188:191], v158 offset:33792
	ds_read_b128 v[192:195], v158 offset:34816
	ds_read_b128 v[196:199], v158 offset:35840
	ds_read_b128 v[200:203], v158 offset:36864
	ds_read_b128 v[204:207], v158 offset:37888
	ds_read_b128 v[208:211], v158 offset:38912
	ds_read_b128 v[212:215], v158 offset:39936
	global_load_lds_dwordx4 v[224:225], off
	v_lshl_add_u64 v[224:225], s[20:21], 0, v[132:133]
	s_mov_b32 m0, s61
	s_nop 0
	global_load_lds_dwordx4 v[224:225], off
	s_waitcnt vmcnt(8)
	s_waitcnt lgkmcnt(0)
	s_barrier
	s_waitcnt lgkmcnt(0)
	v_mfma_i32_16x16x64_i8 v[126:129], v[146:149], v[184:187], v[126:129]
	v_mfma_i32_16x16x64_i8 v[122:125], v[160:163], v[184:187], v[122:125]
	v_mfma_i32_16x16x64_i8 v[110:113], v[146:149], v[192:195], v[110:113]
	v_mfma_i32_16x16x64_i8 v[106:109], v[160:163], v[192:195], v[106:109]
	v_mfma_i32_16x16x64_i8 v[94:97], v[146:149], v[200:203], v[94:97]
	v_mfma_i32_16x16x64_i8 v[90:93], v[160:163], v[200:203], v[90:93]
	v_mfma_i32_16x16x64_i8 v[78:81], v[146:149], v[208:211], v[78:81]
	v_mfma_i32_16x16x64_i8 v[74:77], v[160:163], v[208:211], v[74:77]
	v_mfma_i32_16x16x64_i8 v[126:129], v[150:153], v[188:191], v[126:129]
	v_mfma_i32_16x16x64_i8 v[122:125], v[164:167], v[188:191], v[122:125]
	v_mfma_i32_16x16x64_i8 v[110:113], v[150:153], v[196:199], v[110:113]
	v_mfma_i32_16x16x64_i8 v[106:109], v[164:167], v[196:199], v[106:109]
	v_mfma_i32_16x16x64_i8 v[94:97], v[150:153], v[204:207], v[94:97]
	v_mfma_i32_16x16x64_i8 v[90:93], v[164:167], v[204:207], v[90:93]
	v_mfma_i32_16x16x64_i8 v[78:81], v[150:153], v[212:215], v[78:81]
	v_mfma_i32_16x16x64_i8 v[74:77], v[164:167], v[212:215], v[74:77]
	v_mfma_i32_16x16x64_i8 v[118:121], v[168:171], v[184:187], v[118:121]
	v_mfma_i32_16x16x64_i8 v[114:117], v[176:179], v[184:187], v[114:117]
	v_mfma_i32_16x16x64_i8 v[102:105], v[168:171], v[192:195], v[102:105]
	v_mfma_i32_16x16x64_i8 v[98:101], v[176:179], v[192:195], v[98:101]
	v_mfma_i32_16x16x64_i8 v[86:89], v[168:171], v[200:203], v[86:89]
	v_mfma_i32_16x16x64_i8 v[82:85], v[176:179], v[200:203], v[82:85]
	v_mfma_i32_16x16x64_i8 v[70:73], v[168:171], v[208:211], v[70:73]
	v_mfma_i32_16x16x64_i8 v[66:69], v[176:179], v[208:211], v[66:69]
	v_mfma_i32_16x16x64_i8 v[118:121], v[172:175], v[188:191], v[118:121]
	v_mfma_i32_16x16x64_i8 v[114:117], v[180:183], v[188:191], v[114:117]
	v_mfma_i32_16x16x64_i8 v[102:105], v[172:175], v[196:199], v[102:105]
	v_mfma_i32_16x16x64_i8 v[98:101], v[180:183], v[196:199], v[98:101]
	v_mfma_i32_16x16x64_i8 v[86:89], v[172:175], v[204:207], v[86:89]
	v_mfma_i32_16x16x64_i8 v[82:85], v[180:183], v[204:207], v[82:85]
	v_mfma_i32_16x16x64_i8 v[70:73], v[172:175], v[212:215], v[70:73]
	v_mfma_i32_16x16x64_i8 v[66:69], v[180:183], v[212:215], v[66:69]
	s_barrier
	s_add_i32 s19, s19, s35
	v_lshl_add_u64 v[216:217], v[216:217], 0, s[4:5]
	s_mov_b32 m0, s19
	ds_read_b128 v[184:187], v158 offset:49152
	ds_read_b128 v[188:191], v158 offset:50176
	ds_read_b128 v[192:195], v158 offset:51200
	ds_read_b128 v[196:199], v158 offset:52224
	ds_read_b128 v[200:203], v158 offset:53248
	ds_read_b128 v[204:207], v158 offset:54272
	ds_read_b128 v[208:211], v158 offset:55296
	ds_read_b128 v[212:215], v158 offset:56320
	global_load_lds_dwordx4 v[216:217], off
	s_add_i32 m0, s19, 0x2000
	s_add_u32 s20, s86, 0x80080
	v_lshl_add_u64 v[216:217], v[218:219], 0, s[4:5]
	s_addc_u32 s21, s87, 0
	s_add_i32 s19, s22, s35
	global_load_lds_dwordx4 v[216:217], off
	v_lshl_add_u64 v[216:217], s[20:21], 0, v[134:135]
	s_mov_b32 m0, s19
	s_nop 0
	global_load_lds_dwordx4 v[216:217], off
	v_lshl_add_u64 v[216:217], s[20:21], 0, v[130:131]
	s_add_i32 m0, s19, 0x2000
	s_nop 0
	global_load_lds_dwordx4 v[216:217], off
	v_lshl_add_u64 v[216:217], v[220:221], 0, s[4:5]
	s_mov_b32 m0, s67
	s_nop 0
	global_load_lds_dwordx4 v[216:217], off
	v_lshl_add_u64 v[216:217], v[222:223], 0, s[4:5]
	s_mov_b32 m0, s68
	s_nop 0
	global_load_lds_dwordx4 v[216:217], off
	s_waitcnt vmcnt(8)
	s_waitcnt lgkmcnt(0)
	s_barrier
	s_waitcnt lgkmcnt(0)
	v_mfma_i32_16x16x64_i8 v[62:65], v[146:149], v[184:187], v[62:65]
	v_mfma_i32_16x16x64_i8 v[58:61], v[160:163], v[184:187], v[58:61]
	v_mfma_i32_16x16x64_i8 v[46:49], v[146:149], v[192:195], v[46:49]
	v_mfma_i32_16x16x64_i8 v[42:45], v[160:163], v[192:195], v[42:45]
	v_mfma_i32_16x16x64_i8 v[30:33], v[146:149], v[200:203], v[30:33]
	v_mfma_i32_16x16x64_i8 v[26:29], v[160:163], v[200:203], v[26:29]
	v_mfma_i32_16x16x64_i8 v[14:17], v[146:149], v[208:211], v[14:17]
	v_mfma_i32_16x16x64_i8 v[10:13], v[160:163], v[208:211], v[10:13]
	v_mfma_i32_16x16x64_i8 v[62:65], v[150:153], v[188:191], v[62:65]
	v_mfma_i32_16x16x64_i8 v[58:61], v[164:167], v[188:191], v[58:61]
	v_mfma_i32_16x16x64_i8 v[46:49], v[150:153], v[196:199], v[46:49]
	v_mfma_i32_16x16x64_i8 v[42:45], v[164:167], v[196:199], v[42:45]
	v_mfma_i32_16x16x64_i8 v[30:33], v[150:153], v[204:207], v[30:33]
	v_mfma_i32_16x16x64_i8 v[26:29], v[164:167], v[204:207], v[26:29]
	v_mfma_i32_16x16x64_i8 v[14:17], v[150:153], v[212:215], v[14:17]
	v_mfma_i32_16x16x64_i8 v[10:13], v[164:167], v[212:215], v[10:13]
	v_mfma_i32_16x16x64_i8 v[54:57], v[168:171], v[184:187], v[54:57]
	v_mfma_i32_16x16x64_i8 v[50:53], v[176:179], v[184:187], v[50:53]
	v_mfma_i32_16x16x64_i8 v[38:41], v[168:171], v[192:195], v[38:41]
	v_mfma_i32_16x16x64_i8 v[34:37], v[176:179], v[192:195], v[34:37]
	v_mfma_i32_16x16x64_i8 v[22:25], v[168:171], v[200:203], v[22:25]
	v_mfma_i32_16x16x64_i8 v[18:21], v[176:179], v[200:203], v[18:21]
	v_mfma_i32_16x16x64_i8 v[6:9], v[168:171], v[208:211], v[6:9]
	v_mfma_i32_16x16x64_i8 v[2:5], v[176:179], v[208:211], v[2:5]
	v_mfma_i32_16x16x64_i8 v[54:57], v[172:175], v[188:191], v[54:57]
	v_mfma_i32_16x16x64_i8 v[50:53], v[180:183], v[188:191], v[50:53]
	v_mfma_i32_16x16x64_i8 v[38:41], v[172:175], v[196:199], v[38:41]
	v_mfma_i32_16x16x64_i8 v[34:37], v[180:183], v[196:199], v[34:37]
	v_mfma_i32_16x16x64_i8 v[22:25], v[172:175], v[204:207], v[22:25]
	v_mfma_i32_16x16x64_i8 v[18:21], v[180:183], v[204:207], v[18:21]
	v_mfma_i32_16x16x64_i8 v[6:9], v[172:175], v[212:215], v[6:9]
	v_mfma_i32_16x16x64_i8 v[2:5], v[180:183], v[212:215], v[2:5]
	s_barrier
	s_add_i32 s18, s18, 2
	s_add_u32 s84, s84, 0x100
	s_addc_u32 s85, s85, 0
	s_add_u32 s16, s16, 0x100
	s_addc_u32 s17, s17, 0
	s_cmp_gt_u32 s18, 29
	s_cbranch_scc0 .LBB0_213
	s_setprio 0
	s_and_b64 vcc, exec, s[6:7]
	s_cbranch_vccz .LBB0_216
	s_barrier

.LBB0_361:
	s_add_u32 s6, s6, 0x158080
	s_addc_u32 s7, s7, 0
	s_add_u32 s8, s82, 0x100
	v_mov_b32_e32 v2, 0
	s_addc_u32 s12, s83, 0
	s_mov_b32 s13, -2
	v_mov_b32_e32 v3, v2
	v_mov_b32_e32 v4, v2
	v_mov_b32_e32 v5, v2
	v_mov_b32_e32 v6, v2
	v_mov_b32_e32 v7, v2
	v_mov_b32_e32 v8, v2
	v_mov_b32_e32 v9, v2
	v_mov_b32_e32 v18, v2
	v_mov_b32_e32 v19, v2
	v_mov_b32_e32 v20, v2
	v_mov_b32_e32 v21, v2
	v_mov_b32_e32 v22, v2
	v_mov_b32_e32 v23, v2
	v_mov_b32_e32 v24, v2
	v_mov_b32_e32 v25, v2
	v_mov_b32_e32 v34, v2
	v_mov_b32_e32 v35, v2
	v_mov_b32_e32 v36, v2
	v_mov_b32_e32 v37, v2
	v_mov_b32_e32 v38, v2
	v_mov_b32_e32 v39, v2
	v_mov_b32_e32 v40, v2
	v_mov_b32_e32 v41, v2
	v_mov_b32_e32 v50, v2
	v_mov_b32_e32 v51, v2
	v_mov_b32_e32 v52, v2
	v_mov_b32_e32 v53, v2
	v_mov_b32_e32 v54, v2
	v_mov_b32_e32 v55, v2
	v_mov_b32_e32 v56, v2
	v_mov_b32_e32 v57, v2
	v_mov_b32_e32 v10, v2
	v_mov_b32_e32 v11, v2
	v_mov_b32_e32 v12, v2
	v_mov_b32_e32 v13, v2
	v_mov_b32_e32 v14, v2
	v_mov_b32_e32 v15, v2
	v_mov_b32_e32 v16, v2
	v_mov_b32_e32 v17, v2
	v_mov_b32_e32 v26, v2
	v_mov_b32_e32 v27, v2
	v_mov_b32_e32 v28, v2
	v_mov_b32_e32 v29, v2
	v_mov_b32_e32 v30, v2
	v_mov_b32_e32 v31, v2
	v_mov_b32_e32 v32, v2
	v_mov_b32_e32 v33, v2
	v_mov_b32_e32 v42, v2
	v_mov_b32_e32 v43, v2
	v_mov_b32_e32 v44, v2
	v_mov_b32_e32 v45, v2
	v_mov_b32_e32 v46, v2
	v_mov_b32_e32 v47, v2
	v_mov_b32_e32 v48, v2
	v_mov_b32_e32 v49, v2
	v_mov_b32_e32 v58, v2
	v_mov_b32_e32 v59, v2
	v_mov_b32_e32 v60, v2
	v_mov_b32_e32 v61, v2
	v_mov_b32_e32 v62, v2
	v_mov_b32_e32 v63, v2
	v_mov_b32_e32 v64, v2
	v_mov_b32_e32 v65, v2
	v_mov_b32_e32 v66, v2
	v_mov_b32_e32 v67, v2
	v_mov_b32_e32 v68, v2
	v_mov_b32_e32 v69, v2
	v_mov_b32_e32 v70, v2
	v_mov_b32_e32 v71, v2
	v_mov_b32_e32 v72, v2
	v_mov_b32_e32 v73, v2
	v_mov_b32_e32 v82, v2
	v_mov_b32_e32 v83, v2
	v_mov_b32_e32 v84, v2
	v_mov_b32_e32 v85, v2
	v_mov_b32_e32 v86, v2
	v_mov_b32_e32 v87, v2
	v_mov_b32_e32 v88, v2
	v_mov_b32_e32 v89, v2
	v_mov_b32_e32 v98, v2
	v_mov_b32_e32 v99, v2
	v_mov_b32_e32 v100, v2
	v_mov_b32_e32 v101, v2
	v_mov_b32_e32 v102, v2
	v_mov_b32_e32 v103, v2
	v_mov_b32_e32 v104, v2
	v_mov_b32_e32 v105, v2
	v_mov_b32_e32 v130, v2
	v_mov_b32_e32 v131, v2
	v_mov_b32_e32 v132, v2
	v_mov_b32_e32 v133, v2
	v_mov_b32_e32 v134, v2
	v_mov_b32_e32 v135, v2
	v_mov_b32_e32 v136, v2
	v_mov_b32_e32 v137, v2
	v_mov_b32_e32 v74, v2
	v_mov_b32_e32 v75, v2
	v_mov_b32_e32 v76, v2
	v_mov_b32_e32 v77, v2
	v_mov_b32_e32 v78, v2
	v_mov_b32_e32 v79, v2
	v_mov_b32_e32 v80, v2
	v_mov_b32_e32 v81, v2
	v_mov_b32_e32 v90, v2
	v_mov_b32_e32 v91, v2
	v_mov_b32_e32 v92, v2
	v_mov_b32_e32 v93, v2
	v_mov_b32_e32 v94, v2
	v_mov_b32_e32 v95, v2
	v_mov_b32_e32 v96, v2
	v_mov_b32_e32 v97, v2
	v_mov_b32_e32 v118, v2
	v_mov_b32_e32 v119, v2
	v_mov_b32_e32 v120, v2
	v_mov_b32_e32 v121, v2
	v_mov_b32_e32 v126, v2
	v_mov_b32_e32 v127, v2
	v_mov_b32_e32 v128, v2
	v_mov_b32_e32 v129, v2
	v_mov_b32_e32 v138, v2
	v_mov_b32_e32 v139, v2
	v_mov_b32_e32 v140, v2
	v_mov_b32_e32 v141, v2
	v_mov_b32_e32 v142, v2
	v_mov_b32_e32 v143, v2
	v_mov_b32_e32 v144, v2
	v_mov_b32_e32 v145, v2
	s_and_b64 vcc, exec, s[46:47]
	s_cbranch_vccnz .Lsp_p3
	s_setprio 1
.Lsp_p3:
.LBB0_362:
	ds_read_b128 v[106:109], v168
	ds_read_b128 v[110:113], v168 offset:1024
	ds_read_b128 v[114:117], v168 offset:2048
	ds_read_b128 v[122:125], v168 offset:3072
	ds_read_b128 v[160:163], v169
	ds_read_b128 v[172:175], v169 offset:1024
	ds_read_b128 v[176:179], v169 offset:2048
	ds_read_b128 v[180:183], v169 offset:3072
	s_add_u32 s16, s6, 0xffea8080
	s_addc_u32 s17, s7, -1
	s_cmpk_eq_i32 s13, 0x52
	s_cselect_b32 s85, s51, s17
	s_cselect_b32 s84, s50, s16
	s_cselect_b32 s83, s81, s12
	s_cselect_b32 s82, s80, s8
	v_lshl_add_u64 v[216:217], s[6:7], 0, v[154:155]
	s_add_i32 m0, s56, 0xc000
	ds_read_b128 v[184:187], v170
	ds_read_b128 v[188:191], v170 offset:1024
	ds_read_b128 v[192:195], v170 offset:2048
	ds_read_b128 v[196:199], v170 offset:3072
	ds_read_b128 v[200:203], v170 offset:4096
	ds_read_b128 v[204:207], v170 offset:5120
	ds_read_b128 v[208:211], v170 offset:6144
	ds_read_b128 v[212:215], v170 offset:7168
	global_load_lds_dwordx4 v[216:217], off
	v_lshl_add_u64 v[216:217], s[6:7], 0, v[156:157]
	s_add_i32 m0, s56, 0xe000
	s_nop 0
	global_load_lds_dwordx4 v[216:217], off
	s_waitcnt vmcnt(8)
	s_waitcnt lgkmcnt(0)
	s_barrier
	s_waitcnt lgkmcnt(0)
	v_mfma_i32_16x16x64_i8 v[142:145], v[106:109], v[184:187], v[142:145]
	v_mfma_i32_16x16x64_i8 v[138:141], v[114:117], v[184:187], v[138:141]
	v_mfma_i32_16x16x64_i8 v[126:129], v[106:109], v[192:195], v[126:129]
	v_mfma_i32_16x16x64_i8 v[118:121], v[114:117], v[192:195], v[118:121]
	v_mfma_i32_16x16x64_i8 v[94:97], v[106:109], v[200:203], v[94:97]
	v_mfma_i32_16x16x64_i8 v[90:93], v[114:117], v[200:203], v[90:93]
	v_mfma_i32_16x16x64_i8 v[78:81], v[106:109], v[208:211], v[78:81]
	v_mfma_i32_16x16x64_i8 v[74:77], v[114:117], v[208:211], v[74:77]
	v_mfma_i32_16x16x64_i8 v[142:145], v[110:113], v[188:191], v[142:145]
	v_mfma_i32_16x16x64_i8 v[138:141], v[122:125], v[188:191], v[138:141]
	v_mfma_i32_16x16x64_i8 v[126:129], v[110:113], v[196:199], v[126:129]
	v_mfma_i32_16x16x64_i8 v[118:121], v[122:125], v[196:199], v[118:121]
	v_mfma_i32_16x16x64_i8 v[94:97], v[110:113], v[204:207], v[94:97]
	v_mfma_i32_16x16x64_i8 v[90:93], v[122:125], v[204:207], v[90:93]
	v_mfma_i32_16x16x64_i8 v[78:81], v[110:113], v[212:215], v[78:81]
	v_mfma_i32_16x16x64_i8 v[74:77], v[122:125], v[212:215], v[74:77]
	v_mfma_i32_16x16x64_i8 v[134:137], v[160:163], v[184:187], v[134:137]
	v_mfma_i32_16x16x64_i8 v[130:133], v[176:179], v[184:187], v[130:133]
	v_mfma_i32_16x16x64_i8 v[102:105], v[160:163], v[192:195], v[102:105]
	v_mfma_i32_16x16x64_i8 v[98:101], v[176:179], v[192:195], v[98:101]
	v_mfma_i32_16x16x64_i8 v[86:89], v[160:163], v[200:203], v[86:89]
	v_mfma_i32_16x16x64_i8 v[82:85], v[176:179], v[200:203], v[82:85]
	v_mfma_i32_16x16x64_i8 v[70:73], v[160:163], v[208:211], v[70:73]
	v_mfma_i32_16x16x64_i8 v[66:69], v[176:179], v[208:211], v[66:69]
	v_mfma_i32_16x16x64_i8 v[134:137], v[172:175], v[188:191], v[134:137]
	v_mfma_i32_16x16x64_i8 v[130:133], v[180:183], v[188:191], v[130:133]
	v_mfma_i32_16x16x64_i8 v[102:105], v[172:175], v[196:199], v[102:105]
	v_mfma_i32_16x16x64_i8 v[98:101], v[180:183], v[196:199], v[98:101]
	v_mfma_i32_16x16x64_i8 v[86:89], v[172:175], v[204:207], v[86:89]
	v_mfma_i32_16x16x64_i8 v[82:85], v[180:183], v[204:207], v[82:85]
	v_mfma_i32_16x16x64_i8 v[70:73], v[172:175], v[212:215], v[70:73]
	v_mfma_i32_16x16x64_i8 v[66:69], v[180:183], v[212:215], v[66:69]
	s_barrier
	s_add_i32 s16, s87, s35
	v_lshl_add_u64 v[216:217], s[82:83], 0, v[148:149]
	s_mov_b32 m0, s16
	ds_read_b128 v[184:187], v170 offset:16384
	ds_read_b128 v[188:191], v170 offset:17408
	ds_read_b128 v[192:195], v170 offset:18432
	ds_read_b128 v[196:199], v170 offset:19456
	ds_read_b128 v[200:203], v170 offset:20480
	ds_read_b128 v[204:207], v170 offset:21504
	ds_read_b128 v[208:211], v170 offset:22528
	ds_read_b128 v[212:215], v170 offset:23552
	global_load_lds_dwordx4 v[216:217], off
	s_add_i32 m0, s16, 0x2000
	s_add_u32 s16, s82, 0x158000
	v_lshl_add_u64 v[218:219], s[82:83], 0, v[152:153]
	s_addc_u32 s17, s83, 0
	s_add_i32 s18, s88, s35
	global_load_lds_dwordx4 v[218:219], off
	v_lshl_add_u64 v[220:221], s[16:17], 0, v[148:149]
	s_mov_b32 m0, s18
	v_lshl_add_u64 v[222:223], s[84:85], 0, v[150:151]
	global_load_lds_dwordx4 v[220:221], off
	v_lshl_add_u64 v[220:221], s[16:17], 0, v[152:153]
	s_add_i32 m0, s18, 0x2000
	s_nop 0
	global_load_lds_dwordx4 v[220:221], off
	v_lshl_add_u64 v[220:221], s[84:85], 0, v[146:147]
	s_mov_b32 m0, s56
	s_nop 0
	global_load_lds_dwordx4 v[220:221], off
	s_mov_b32 m0, s57
	s_nop 0
	global_load_lds_dwordx4 v[222:223], off
	s_waitcnt vmcnt(8)
	s_waitcnt lgkmcnt(0)
	s_barrier
	s_waitcnt lgkmcnt(0)
	v_mfma_i32_16x16x64_i8 v[62:65], v[106:109], v[184:187], v[62:65]
	v_mfma_i32_16x16x64_i8 v[58:61], v[114:117], v[184:187], v[58:61]
	v_mfma_i32_16x16x64_i8 v[46:49], v[106:109], v[192:195], v[46:49]
	v_mfma_i32_16x16x64_i8 v[42:45], v[114:117], v[192:195], v[42:45]
	v_mfma_i32_16x16x64_i8 v[30:33], v[106:109], v[200:203], v[30:33]
	v_mfma_i32_16x16x64_i8 v[26:29], v[114:117], v[200:203], v[26:29]
	v_mfma_i32_16x16x64_i8 v[14:17], v[106:109], v[208:211], v[14:17]
	v_mfma_i32_16x16x64_i8 v[10:13], v[114:117], v[208:211], v[10:13]
	v_mfma_i32_16x16x64_i8 v[62:65], v[110:113], v[188:191], v[62:65]
	v_mfma_i32_16x16x64_i8 v[58:61], v[122:125], v[188:191], v[58:61]
	v_mfma_i32_16x16x64_i8 v[46:49], v[110:113], v[196:199], v[46:49]
	v_mfma_i32_16x16x64_i8 v[42:45], v[122:125], v[196:199], v[42:45]
	v_mfma_i32_16x16x64_i8 v[30:33], v[110:113], v[204:207], v[30:33]
	v_mfma_i32_16x16x64_i8 v[26:29], v[122:125], v[204:207], v[26:29]
	v_mfma_i32_16x16x64_i8 v[14:17], v[110:113], v[212:215], v[14:17]
	v_mfma_i32_16x16x64_i8 v[10:13], v[122:125], v[212:215], v[10:13]
	v_mfma_i32_16x16x64_i8 v[54:57], v[160:163], v[184:187], v[54:57]
	v_mfma_i32_16x16x64_i8 v[50:53], v[176:179], v[184:187], v[50:53]
	v_mfma_i32_16x16x64_i8 v[38:41], v[160:163], v[192:195], v[38:41]
	v_mfma_i32_16x16x64_i8 v[34:37], v[176:179], v[192:195], v[34:37]
	v_mfma_i32_16x16x64_i8 v[22:25], v[160:163], v[200:203], v[22:25]
	v_mfma_i32_16x16x64_i8 v[18:21], v[176:179], v[200:203], v[18:21]
	v_mfma_i32_16x16x64_i8 v[6:9], v[160:163], v[208:211], v[6:9]
	v_mfma_i32_16x16x64_i8 v[2:5], v[176:179], v[208:211], v[2:5]
	v_mfma_i32_16x16x64_i8 v[54:57], v[172:175], v[188:191], v[54:57]
	v_mfma_i32_16x16x64_i8 v[50:53], v[180:183], v[188:191], v[50:53]
	v_mfma_i32_16x16x64_i8 v[38:41], v[172:175], v[196:199], v[38:41]
	v_mfma_i32_16x16x64_i8 v[34:37], v[180:183], v[196:199], v[34:37]
	v_mfma_i32_16x16x64_i8 v[22:25], v[172:175], v[204:207], v[22:25]
	v_mfma_i32_16x16x64_i8 v[18:21], v[180:183], v[204:207], v[18:21]
	v_mfma_i32_16x16x64_i8 v[6:9], v[172:175], v[212:215], v[6:9]
	v_mfma_i32_16x16x64_i8 v[2:5], v[180:183], v[212:215], v[2:5]
	s_barrier
	s_add_i32 s18, 0, 0x18000
	s_add_i32 s19, 0, 0x1c000
	v_add_u32_e32 v122, s18, v165
	v_add_u32_e32 v164, s19, v165
	ds_read_b128 v[106:109], v122
	ds_read_b128 v[110:113], v122 offset:1024
	ds_read_b128 v[114:117], v122 offset:2048
	ds_read_b128 v[122:125], v122 offset:3072
	ds_read_b128 v[160:163], v164
	ds_read_b128 v[172:175], v164 offset:1024
	ds_read_b128 v[176:179], v164 offset:2048
	ds_read_b128 v[180:183], v164 offset:3072
	s_add_u32 s16, s84, 0x158000
	s_addc_u32 s17, s85, 0
	s_mov_b32 m0, s58
	v_lshl_add_u64 v[224:225], s[16:17], 0, v[146:147]
	ds_read_b128 v[184:187], v170 offset:32768
	ds_read_b128 v[188:191], v170 offset:33792
	ds_read_b128 v[192:195], v170 offset:34816
	ds_read_b128 v[196:199], v170 offset:35840
	ds_read_b128 v[200:203], v170 offset:36864
	ds_read_b128 v[204:207], v170 offset:37888
	ds_read_b128 v[208:211], v170 offset:38912
	ds_read_b128 v[212:215], v170 offset:39936
	global_load_lds_dwordx4 v[224:225], off
	v_lshl_add_u64 v[224:225], s[16:17], 0, v[150:151]
	s_mov_b32 m0, s59
	s_nop 0
	global_load_lds_dwordx4 v[224:225], off
	s_waitcnt vmcnt(8)
	s_waitcnt lgkmcnt(0)
	s_barrier
	s_waitcnt lgkmcnt(0)
	v_mfma_i32_16x16x64_i8 v[142:145], v[106:109], v[184:187], v[142:145]
	v_mfma_i32_16x16x64_i8 v[138:141], v[114:117], v[184:187], v[138:141]
	v_mfma_i32_16x16x64_i8 v[126:129], v[106:109], v[192:195], v[126:129]
	v_mfma_i32_16x16x64_i8 v[118:121], v[114:117], v[192:195], v[118:121]
	v_mfma_i32_16x16x64_i8 v[94:97], v[106:109], v[200:203], v[94:97]
	v_mfma_i32_16x16x64_i8 v[90:93], v[114:117], v[200:203], v[90:93]
	v_mfma_i32_16x16x64_i8 v[78:81], v[106:109], v[208:211], v[78:81]
	v_mfma_i32_16x16x64_i8 v[74:77], v[114:117], v[208:211], v[74:77]
	v_mfma_i32_16x16x64_i8 v[142:145], v[110:113], v[188:191], v[142:145]
	v_mfma_i32_16x16x64_i8 v[138:141], v[122:125], v[188:191], v[138:141]
	v_mfma_i32_16x16x64_i8 v[126:129], v[110:113], v[196:199], v[126:129]
	v_mfma_i32_16x16x64_i8 v[118:121], v[122:125], v[196:199], v[118:121]
	v_mfma_i32_16x16x64_i8 v[94:97], v[110:113], v[204:207], v[94:97]
	v_mfma_i32_16x16x64_i8 v[90:93], v[122:125], v[204:207], v[90:93]
	v_mfma_i32_16x16x64_i8 v[78:81], v[110:113], v[212:215], v[78:81]
	v_mfma_i32_16x16x64_i8 v[74:77], v[122:125], v[212:215], v[74:77]
	v_mfma_i32_16x16x64_i8 v[134:137], v[160:163], v[184:187], v[134:137]
	v_mfma_i32_16x16x64_i8 v[130:133], v[176:179], v[184:187], v[130:133]
	v_mfma_i32_16x16x64_i8 v[102:105], v[160:163], v[192:195], v[102:105]
	v_mfma_i32_16x16x64_i8 v[98:101], v[176:179], v[192:195], v[98:101]
	v_mfma_i32_16x16x64_i8 v[86:89], v[160:163], v[200:203], v[86:89]
	v_mfma_i32_16x16x64_i8 v[82:85], v[176:179], v[200:203], v[82:85]
	v_mfma_i32_16x16x64_i8 v[70:73], v[160:163], v[208:211], v[70:73]
	v_mfma_i32_16x16x64_i8 v[66:69], v[176:179], v[208:211], v[66:69]
	v_mfma_i32_16x16x64_i8 v[134:137], v[172:175], v[188:191], v[134:137]
	v_mfma_i32_16x16x64_i8 v[130:133], v[180:183], v[188:191], v[130:133]
	v_mfma_i32_16x16x64_i8 v[102:105], v[172:175], v[196:199], v[102:105]
	v_mfma_i32_16x16x64_i8 v[98:101], v[180:183], v[196:199], v[98:101]
	v_mfma_i32_16x16x64_i8 v[86:89], v[172:175], v[204:207], v[86:89]
	v_mfma_i32_16x16x64_i8 v[82:85], v[180:183], v[204:207], v[82:85]
	v_mfma_i32_16x16x64_i8 v[70:73], v[172:175], v[212:215], v[70:73]
	v_mfma_i32_16x16x64_i8 v[66:69], v[180:183], v[212:215], v[66:69]
	s_barrier
	s_add_i32 s16, s18, s35
	v_lshl_add_u64 v[216:217], v[216:217], 0, s[44:45]
	s_mov_b32 m0, s16
	ds_read_b128 v[184:187], v170 offset:49152
	ds_read_b128 v[188:191], v170 offset:50176
	ds_read_b128 v[192:195], v170 offset:51200
	ds_read_b128 v[196:199], v170 offset:52224
	ds_read_b128 v[200:203], v170 offset:53248
	ds_read_b128 v[204:207], v170 offset:54272
	ds_read_b128 v[208:211], v170 offset:55296
	ds_read_b128 v[212:215], v170 offset:56320
	global_load_lds_dwordx4 v[216:217], off
	s_add_i32 m0, s16, 0x2000
	s_add_u32 s16, s82, 0x158080
	v_lshl_add_u64 v[216:217], v[218:219], 0, s[44:45]
	s_addc_u32 s17, s83, 0
	s_add_i32 s18, s19, s35
	global_load_lds_dwordx4 v[216:217], off
	v_lshl_add_u64 v[216:217], s[16:17], 0, v[148:149]
	s_mov_b32 m0, s18
	s_nop 0
	global_load_lds_dwordx4 v[216:217], off
	v_lshl_add_u64 v[216:217], s[16:17], 0, v[152:153]
	s_add_i32 m0, s18, 0x2000
	s_nop 0
	global_load_lds_dwordx4 v[216:217], off
	v_lshl_add_u64 v[216:217], v[220:221], 0, s[44:45]
	s_mov_b32 m0, s61
	s_nop 0
	global_load_lds_dwordx4 v[216:217], off
	v_lshl_add_u64 v[216:217], v[222:223], 0, s[44:45]
	s_mov_b32 m0, s66
	s_nop 0
	global_load_lds_dwordx4 v[216:217], off
	s_waitcnt vmcnt(8)
	s_waitcnt lgkmcnt(0)
	s_barrier
	s_waitcnt lgkmcnt(0)
	v_mfma_i32_16x16x64_i8 v[62:65], v[106:109], v[184:187], v[62:65]
	v_mfma_i32_16x16x64_i8 v[58:61], v[114:117], v[184:187], v[58:61]
	v_mfma_i32_16x16x64_i8 v[46:49], v[106:109], v[192:195], v[46:49]
	v_mfma_i32_16x16x64_i8 v[42:45], v[114:117], v[192:195], v[42:45]
	v_mfma_i32_16x16x64_i8 v[30:33], v[106:109], v[200:203], v[30:33]
	v_mfma_i32_16x16x64_i8 v[26:29], v[114:117], v[200:203], v[26:29]
	v_mfma_i32_16x16x64_i8 v[14:17], v[106:109], v[208:211], v[14:17]
	v_mfma_i32_16x16x64_i8 v[10:13], v[114:117], v[208:211], v[10:13]
	v_mfma_i32_16x16x64_i8 v[62:65], v[110:113], v[188:191], v[62:65]
	v_mfma_i32_16x16x64_i8 v[58:61], v[122:125], v[188:191], v[58:61]
	v_mfma_i32_16x16x64_i8 v[46:49], v[110:113], v[196:199], v[46:49]
	v_mfma_i32_16x16x64_i8 v[42:45], v[122:125], v[196:199], v[42:45]
	v_mfma_i32_16x16x64_i8 v[30:33], v[110:113], v[204:207], v[30:33]
	v_mfma_i32_16x16x64_i8 v[26:29], v[122:125], v[204:207], v[26:29]
	v_mfma_i32_16x16x64_i8 v[14:17], v[110:113], v[212:215], v[14:17]
	v_mfma_i32_16x16x64_i8 v[10:13], v[122:125], v[212:215], v[10:13]
	v_mfma_i32_16x16x64_i8 v[54:57], v[160:163], v[184:187], v[54:57]
	v_mfma_i32_16x16x64_i8 v[50:53], v[176:179], v[184:187], v[50:53]
	v_mfma_i32_16x16x64_i8 v[38:41], v[160:163], v[192:195], v[38:41]
	v_mfma_i32_16x16x64_i8 v[34:37], v[176:179], v[192:195], v[34:37]
	v_mfma_i32_16x16x64_i8 v[22:25], v[160:163], v[200:203], v[22:25]
	v_mfma_i32_16x16x64_i8 v[18:21], v[176:179], v[200:203], v[18:21]
	v_mfma_i32_16x16x64_i8 v[6:9], v[160:163], v[208:211], v[6:9]
	v_mfma_i32_16x16x64_i8 v[2:5], v[176:179], v[208:211], v[2:5]
	v_mfma_i32_16x16x64_i8 v[54:57], v[172:175], v[188:191], v[54:57]
	v_mfma_i32_16x16x64_i8 v[50:53], v[180:183], v[188:191], v[50:53]
	v_mfma_i32_16x16x64_i8 v[38:41], v[172:175], v[196:199], v[38:41]
	v_mfma_i32_16x16x64_i8 v[34:37], v[180:183], v[196:199], v[34:37]
	v_mfma_i32_16x16x64_i8 v[22:25], v[172:175], v[204:207], v[22:25]
	v_mfma_i32_16x16x64_i8 v[18:21], v[180:183], v[204:207], v[18:21]
	v_mfma_i32_16x16x64_i8 v[6:9], v[172:175], v[212:215], v[6:9]
	v_mfma_i32_16x16x64_i8 v[2:5], v[180:183], v[212:215], v[2:5]
	s_barrier
	s_add_i32 s13, s13, 2
	s_add_u32 s6, s6, 0x100
	s_addc_u32 s7, s7, 0
	s_add_u32 s8, s8, 0x100
	s_addc_u32 s12, s12, 0
	s_cmpk_gt_u32 s13, 0x53
	s_cbranch_scc0 .LBB0_362
	s_setprio 0
	s_and_b64 vcc, exec, s[46:47]
	s_cbranch_vccz .LBB0_365
	s_barrier

.LBB0_540:
	s_ashr_i32 s49, s48, 31
	s_lshl_b64 s[8:9], s[48:49], 21
	s_add_u32 s50, s78, s8
	s_addc_u32 s51, s79, s9
	s_and_b64 s[8:9], s[2:3], exec
	s_cselect_b32 s5, s51, s85
	s_cselect_b32 s8, s50, s84
	s_ashr_i32 s47, s46, 31
	s_lshl_b64 s[12:13], s[46:47], 21
	s_add_u32 s80, s76, s12
	s_addc_u32 s81, s77, s13
	s_and_b64 s[12:13], s[2:3], exec
	s_cselect_b32 s9, s81, s87
	s_cselect_b32 s12, s80, s86
	s_add_u32 s84, s84, 0x100080
	s_addc_u32 s85, s85, 0
	s_add_u32 s13, s86, 0x100
	v_mov_b32_e32 v2, 0
	s_addc_u32 s16, s87, 0
	s_mov_b32 s17, -2
	v_mov_b32_e32 v3, v2
	v_mov_b32_e32 v4, v2
	v_mov_b32_e32 v5, v2
	v_mov_b32_e32 v6, v2
	v_mov_b32_e32 v7, v2
	v_mov_b32_e32 v8, v2
	v_mov_b32_e32 v9, v2
	v_mov_b32_e32 v18, v2
	v_mov_b32_e32 v19, v2
	v_mov_b32_e32 v20, v2
	v_mov_b32_e32 v21, v2
	v_mov_b32_e32 v22, v2
	v_mov_b32_e32 v23, v2
	v_mov_b32_e32 v24, v2
	v_mov_b32_e32 v25, v2
	v_mov_b32_e32 v34, v2
	v_mov_b32_e32 v35, v2
	v_mov_b32_e32 v36, v2
	v_mov_b32_e32 v37, v2
	v_mov_b32_e32 v38, v2
	v_mov_b32_e32 v39, v2
	v_mov_b32_e32 v40, v2
	v_mov_b32_e32 v41, v2
	v_mov_b32_e32 v50, v2
	v_mov_b32_e32 v51, v2
	v_mov_b32_e32 v52, v2
	v_mov_b32_e32 v53, v2
	v_mov_b32_e32 v54, v2
	v_mov_b32_e32 v55, v2
	v_mov_b32_e32 v56, v2
	v_mov_b32_e32 v57, v2
	v_mov_b32_e32 v10, v2
	v_mov_b32_e32 v11, v2
	v_mov_b32_e32 v12, v2
	v_mov_b32_e32 v13, v2
	v_mov_b32_e32 v14, v2
	v_mov_b32_e32 v15, v2
	v_mov_b32_e32 v16, v2
	v_mov_b32_e32 v17, v2
	v_mov_b32_e32 v26, v2
	v_mov_b32_e32 v27, v2
	v_mov_b32_e32 v28, v2
	v_mov_b32_e32 v29, v2
	v_mov_b32_e32 v30, v2
	v_mov_b32_e32 v31, v2
	v_mov_b32_e32 v32, v2
	v_mov_b32_e32 v33, v2
	v_mov_b32_e32 v42, v2
	v_mov_b32_e32 v43, v2
	v_mov_b32_e32 v44, v2
	v_mov_b32_e32 v45, v2
	v_mov_b32_e32 v46, v2
	v_mov_b32_e32 v47, v2
	v_mov_b32_e32 v48, v2
	v_mov_b32_e32 v49, v2
	v_mov_b32_e32 v58, v2
	v_mov_b32_e32 v59, v2
	v_mov_b32_e32 v60, v2
	v_mov_b32_e32 v61, v2
	v_mov_b32_e32 v62, v2
	v_mov_b32_e32 v63, v2
	v_mov_b32_e32 v64, v2
	v_mov_b32_e32 v65, v2
	v_mov_b32_e32 v66, v2
	v_mov_b32_e32 v67, v2
	v_mov_b32_e32 v68, v2
	v_mov_b32_e32 v69, v2
	v_mov_b32_e32 v70, v2
	v_mov_b32_e32 v71, v2
	v_mov_b32_e32 v72, v2
	v_mov_b32_e32 v73, v2
	v_mov_b32_e32 v82, v2
	v_mov_b32_e32 v83, v2
	v_mov_b32_e32 v84, v2
	v_mov_b32_e32 v85, v2
	v_mov_b32_e32 v86, v2
	v_mov_b32_e32 v87, v2
	v_mov_b32_e32 v88, v2
	v_mov_b32_e32 v89, v2
	v_mov_b32_e32 v98, v2
	v_mov_b32_e32 v99, v2
	v_mov_b32_e32 v100, v2
	v_mov_b32_e32 v101, v2
	v_mov_b32_e32 v102, v2
	v_mov_b32_e32 v103, v2
	v_mov_b32_e32 v104, v2
	v_mov_b32_e32 v105, v2
	v_mov_b32_e32 v114, v2
	v_mov_b32_e32 v115, v2
	v_mov_b32_e32 v116, v2
	v_mov_b32_e32 v117, v2
	v_mov_b32_e32 v118, v2
	v_mov_b32_e32 v119, v2
	v_mov_b32_e32 v120, v2
	v_mov_b32_e32 v121, v2
	v_mov_b32_e32 v74, v2
	v_mov_b32_e32 v75, v2
	v_mov_b32_e32 v76, v2
	v_mov_b32_e32 v77, v2
	v_mov_b32_e32 v78, v2
	v_mov_b32_e32 v79, v2
	v_mov_b32_e32 v80, v2
	v_mov_b32_e32 v81, v2
	v_mov_b32_e32 v90, v2
	v_mov_b32_e32 v91, v2
	v_mov_b32_e32 v92, v2
	v_mov_b32_e32 v93, v2
	v_mov_b32_e32 v94, v2
	v_mov_b32_e32 v95, v2
	v_mov_b32_e32 v96, v2
	v_mov_b32_e32 v97, v2
	v_mov_b32_e32 v106, v2
	v_mov_b32_e32 v107, v2
	v_mov_b32_e32 v108, v2
	v_mov_b32_e32 v109, v2
	v_mov_b32_e32 v110, v2
	v_mov_b32_e32 v111, v2
	v_mov_b32_e32 v112, v2
	v_mov_b32_e32 v113, v2
	v_mov_b32_e32 v122, v2
	v_mov_b32_e32 v123, v2
	v_mov_b32_e32 v124, v2
	v_mov_b32_e32 v125, v2
	v_mov_b32_e32 v126, v2
	v_mov_b32_e32 v127, v2
	v_mov_b32_e32 v128, v2
	v_mov_b32_e32 v129, v2
	s_and_b64 vcc, exec, s[42:43]
	s_cbranch_vccnz .Lsp_p5
	s_setprio 1
.Lsp_p5:
.LBB0_541:
	ds_read_b128 v[146:149], v154
	ds_read_b128 v[158:161], v154 offset:1024
	ds_read_b128 v[162:165], v154 offset:2048
	ds_read_b128 v[166:169], v154 offset:3072
	ds_read_b128 v[170:173], v155
	ds_read_b128 v[174:177], v155 offset:1024
	ds_read_b128 v[178:181], v155 offset:2048
	ds_read_b128 v[182:185], v155 offset:3072
	s_add_u32 s18, s84, 0xfff00080
	s_addc_u32 s19, s85, -1
	s_cmp_eq_u32 s17, 60
	s_cselect_b32 s89, s5, s19
	s_cselect_b32 s88, s8, s18
	s_cselect_b32 s87, s9, s16
	s_cselect_b32 s86, s12, s13
	v_lshl_add_u64 v[218:219], s[84:85], 0, v[138:139]
	s_add_i32 m0, s56, 0xc000
	ds_read_b128 v[186:189], v156
	ds_read_b128 v[190:193], v156 offset:1024
	ds_read_b128 v[194:197], v156 offset:2048
	ds_read_b128 v[198:201], v156 offset:3072
	ds_read_b128 v[202:205], v156 offset:4096
	ds_read_b128 v[206:209], v156 offset:5120
	ds_read_b128 v[210:213], v156 offset:6144
	ds_read_b128 v[214:217], v156 offset:7168
	global_load_lds_dwordx4 v[218:219], off
	v_lshl_add_u64 v[218:219], s[84:85], 0, v[140:141]
	s_add_i32 m0, s56, 0xe000
	s_nop 0
	global_load_lds_dwordx4 v[218:219], off
	s_waitcnt vmcnt(8)
	s_waitcnt lgkmcnt(0)
	s_barrier
	s_waitcnt lgkmcnt(0)
	v_mfma_f32_16x16x32_bf16 v[126:129], v[146:149], v[186:189], v[126:129]
	v_mfma_f32_16x16x32_bf16 v[122:125], v[162:165], v[186:189], v[122:125]
	v_mfma_f32_16x16x32_bf16 v[110:113], v[146:149], v[194:197], v[110:113]
	v_mfma_f32_16x16x32_bf16 v[106:109], v[162:165], v[194:197], v[106:109]
	v_mfma_f32_16x16x32_bf16 v[94:97], v[146:149], v[202:205], v[94:97]
	v_mfma_f32_16x16x32_bf16 v[90:93], v[162:165], v[202:205], v[90:93]
	v_mfma_f32_16x16x32_bf16 v[78:81], v[146:149], v[210:213], v[78:81]
	v_mfma_f32_16x16x32_bf16 v[74:77], v[162:165], v[210:213], v[74:77]
	v_mfma_f32_16x16x32_bf16 v[126:129], v[158:161], v[190:193], v[126:129]
	v_mfma_f32_16x16x32_bf16 v[122:125], v[166:169], v[190:193], v[122:125]
	v_mfma_f32_16x16x32_bf16 v[110:113], v[158:161], v[198:201], v[110:113]
	v_mfma_f32_16x16x32_bf16 v[106:109], v[166:169], v[198:201], v[106:109]
	v_mfma_f32_16x16x32_bf16 v[94:97], v[158:161], v[206:209], v[94:97]
	v_mfma_f32_16x16x32_bf16 v[90:93], v[166:169], v[206:209], v[90:93]
	v_mfma_f32_16x16x32_bf16 v[78:81], v[158:161], v[214:217], v[78:81]
	v_mfma_f32_16x16x32_bf16 v[74:77], v[166:169], v[214:217], v[74:77]
	v_mfma_f32_16x16x32_bf16 v[118:121], v[170:173], v[186:189], v[118:121]
	v_mfma_f32_16x16x32_bf16 v[114:117], v[178:181], v[186:189], v[114:117]
	v_mfma_f32_16x16x32_bf16 v[102:105], v[170:173], v[194:197], v[102:105]
	v_mfma_f32_16x16x32_bf16 v[98:101], v[178:181], v[194:197], v[98:101]
	v_mfma_f32_16x16x32_bf16 v[86:89], v[170:173], v[202:205], v[86:89]
	v_mfma_f32_16x16x32_bf16 v[82:85], v[178:181], v[202:205], v[82:85]
	v_mfma_f32_16x16x32_bf16 v[70:73], v[170:173], v[210:213], v[70:73]
	v_mfma_f32_16x16x32_bf16 v[66:69], v[178:181], v[210:213], v[66:69]
	v_mfma_f32_16x16x32_bf16 v[118:121], v[174:177], v[190:193], v[118:121]
	v_mfma_f32_16x16x32_bf16 v[114:117], v[182:185], v[190:193], v[114:117]
	v_mfma_f32_16x16x32_bf16 v[102:105], v[174:177], v[198:201], v[102:105]
	v_mfma_f32_16x16x32_bf16 v[98:101], v[182:185], v[198:201], v[98:101]
	v_mfma_f32_16x16x32_bf16 v[86:89], v[174:177], v[206:209], v[86:89]
	v_mfma_f32_16x16x32_bf16 v[82:85], v[182:185], v[206:209], v[82:85]
	v_mfma_f32_16x16x32_bf16 v[70:73], v[174:177], v[214:217], v[70:73]
	v_mfma_f32_16x16x32_bf16 v[66:69], v[182:185], v[214:217], v[66:69]
	s_barrier
	s_add_i32 s18, s83, s35
	v_lshl_add_u64 v[218:219], s[86:87], 0, v[132:133]
	s_mov_b32 m0, s18
	ds_read_b128 v[186:189], v156 offset:16384
	ds_read_b128 v[190:193], v156 offset:17408
	ds_read_b128 v[194:197], v156 offset:18432
	ds_read_b128 v[198:201], v156 offset:19456
	ds_read_b128 v[202:205], v156 offset:20480
	ds_read_b128 v[206:209], v156 offset:21504
	ds_read_b128 v[210:213], v156 offset:22528
	ds_read_b128 v[214:217], v156 offset:23552
	global_load_lds_dwordx4 v[218:219], off
	s_add_i32 m0, s18, 0x2000
	s_add_u32 s18, s86, 0x100000
	v_lshl_add_u64 v[220:221], s[86:87], 0, v[136:137]
	s_addc_u32 s19, s87, 0
	s_add_i32 s20, s90, s35
	global_load_lds_dwordx4 v[220:221], off
	v_lshl_add_u64 v[222:223], s[18:19], 0, v[132:133]
	s_mov_b32 m0, s20
	v_lshl_add_u64 v[224:225], s[88:89], 0, v[134:135]
	global_load_lds_dwordx4 v[222:223], off
	v_lshl_add_u64 v[222:223], s[18:19], 0, v[136:137]
	s_add_i32 m0, s20, 0x2000
	s_nop 0
	global_load_lds_dwordx4 v[222:223], off
	v_lshl_add_u64 v[222:223], s[88:89], 0, v[130:131]
	s_mov_b32 m0, s56
	s_nop 0
	global_load_lds_dwordx4 v[222:223], off
	s_mov_b32 m0, s57
	s_nop 0
	global_load_lds_dwordx4 v[224:225], off
	s_waitcnt vmcnt(8)
	s_waitcnt lgkmcnt(0)
	s_barrier
	s_waitcnt lgkmcnt(0)
	v_mfma_f32_16x16x32_bf16 v[62:65], v[146:149], v[186:189], v[62:65]
	v_mfma_f32_16x16x32_bf16 v[58:61], v[162:165], v[186:189], v[58:61]
	v_mfma_f32_16x16x32_bf16 v[46:49], v[146:149], v[194:197], v[46:49]
	v_mfma_f32_16x16x32_bf16 v[42:45], v[162:165], v[194:197], v[42:45]
	v_mfma_f32_16x16x32_bf16 v[30:33], v[146:149], v[202:205], v[30:33]
	v_mfma_f32_16x16x32_bf16 v[26:29], v[162:165], v[202:205], v[26:29]
	v_mfma_f32_16x16x32_bf16 v[14:17], v[146:149], v[210:213], v[14:17]
	v_mfma_f32_16x16x32_bf16 v[10:13], v[162:165], v[210:213], v[10:13]
	v_mfma_f32_16x16x32_bf16 v[62:65], v[158:161], v[190:193], v[62:65]
	v_mfma_f32_16x16x32_bf16 v[58:61], v[166:169], v[190:193], v[58:61]
	v_mfma_f32_16x16x32_bf16 v[46:49], v[158:161], v[198:201], v[46:49]
	v_mfma_f32_16x16x32_bf16 v[42:45], v[166:169], v[198:201], v[42:45]
	v_mfma_f32_16x16x32_bf16 v[30:33], v[158:161], v[206:209], v[30:33]
	v_mfma_f32_16x16x32_bf16 v[26:29], v[166:169], v[206:209], v[26:29]
	v_mfma_f32_16x16x32_bf16 v[14:17], v[158:161], v[214:217], v[14:17]
	v_mfma_f32_16x16x32_bf16 v[10:13], v[166:169], v[214:217], v[10:13]
	v_mfma_f32_16x16x32_bf16 v[54:57], v[170:173], v[186:189], v[54:57]
	v_mfma_f32_16x16x32_bf16 v[50:53], v[178:181], v[186:189], v[50:53]
	v_mfma_f32_16x16x32_bf16 v[38:41], v[170:173], v[194:197], v[38:41]
	v_mfma_f32_16x16x32_bf16 v[34:37], v[178:181], v[194:197], v[34:37]
	v_mfma_f32_16x16x32_bf16 v[22:25], v[170:173], v[202:205], v[22:25]
	v_mfma_f32_16x16x32_bf16 v[18:21], v[178:181], v[202:205], v[18:21]
	v_mfma_f32_16x16x32_bf16 v[6:9], v[170:173], v[210:213], v[6:9]
	v_mfma_f32_16x16x32_bf16 v[2:5], v[178:181], v[210:213], v[2:5]
	v_mfma_f32_16x16x32_bf16 v[54:57], v[174:177], v[190:193], v[54:57]
	v_mfma_f32_16x16x32_bf16 v[50:53], v[182:185], v[190:193], v[50:53]
	v_mfma_f32_16x16x32_bf16 v[38:41], v[174:177], v[198:201], v[38:41]
	v_mfma_f32_16x16x32_bf16 v[34:37], v[182:185], v[198:201], v[34:37]
	v_mfma_f32_16x16x32_bf16 v[22:25], v[174:177], v[206:209], v[22:25]
	v_mfma_f32_16x16x32_bf16 v[18:21], v[182:185], v[206:209], v[18:21]
	v_mfma_f32_16x16x32_bf16 v[6:9], v[174:177], v[214:217], v[6:9]
	v_mfma_f32_16x16x32_bf16 v[2:5], v[182:185], v[214:217], v[2:5]
	s_barrier
	s_add_i32 s20, 0, 0x18000
	v_add_u32_e32 v150, s20, v151
	s_add_i32 s21, 0, 0x1c000
	ds_read_b128 v[146:149], v150
	ds_read_b128 v[158:161], v150 offset:1024
	ds_read_b128 v[162:165], v150 offset:2048
	ds_read_b128 v[166:169], v150 offset:3072
	v_add_u32_e32 v150, s21, v151
	ds_read_b128 v[170:173], v150
	ds_read_b128 v[174:177], v150 offset:1024
	ds_read_b128 v[178:181], v150 offset:2048
	ds_read_b128 v[182:185], v150 offset:3072
	s_add_u32 s18, s88, 0x100000
	s_addc_u32 s19, s89, 0
	s_mov_b32 m0, s58
	v_lshl_add_u64 v[228:229], s[18:19], 0, v[130:131]
	ds_read_b128 v[186:189], v156 offset:32768
	ds_read_b128 v[190:193], v156 offset:33792
	ds_read_b128 v[194:197], v156 offset:34816
	ds_read_b128 v[198:201], v156 offset:35840
	ds_read_b128 v[202:205], v156 offset:36864
	ds_read_b128 v[206:209], v156 offset:37888
	ds_read_b128 v[210:213], v156 offset:38912
	ds_read_b128 v[214:217], v156 offset:39936
	global_load_lds_dwordx4 v[228:229], off
	v_lshl_add_u64 v[228:229], s[18:19], 0, v[134:135]
	s_mov_b32 m0, s59
	s_nop 0
	global_load_lds_dwordx4 v[228:229], off
	s_waitcnt vmcnt(8)
	s_waitcnt lgkmcnt(0)
	s_barrier
	s_waitcnt lgkmcnt(0)
	v_mfma_f32_16x16x32_bf16 v[126:129], v[146:149], v[186:189], v[126:129]
	v_mfma_f32_16x16x32_bf16 v[122:125], v[162:165], v[186:189], v[122:125]
	v_mfma_f32_16x16x32_bf16 v[110:113], v[146:149], v[194:197], v[110:113]
	v_mfma_f32_16x16x32_bf16 v[106:109], v[162:165], v[194:197], v[106:109]
	v_mfma_f32_16x16x32_bf16 v[94:97], v[146:149], v[202:205], v[94:97]
	v_mfma_f32_16x16x32_bf16 v[90:93], v[162:165], v[202:205], v[90:93]
	v_mfma_f32_16x16x32_bf16 v[78:81], v[146:149], v[210:213], v[78:81]
	v_mfma_f32_16x16x32_bf16 v[74:77], v[162:165], v[210:213], v[74:77]
	v_mfma_f32_16x16x32_bf16 v[126:129], v[158:161], v[190:193], v[126:129]
	v_mfma_f32_16x16x32_bf16 v[122:125], v[166:169], v[190:193], v[122:125]
	v_mfma_f32_16x16x32_bf16 v[110:113], v[158:161], v[198:201], v[110:113]
	v_mfma_f32_16x16x32_bf16 v[106:109], v[166:169], v[198:201], v[106:109]
	v_mfma_f32_16x16x32_bf16 v[94:97], v[158:161], v[206:209], v[94:97]
	v_mfma_f32_16x16x32_bf16 v[90:93], v[166:169], v[206:209], v[90:93]
	v_mfma_f32_16x16x32_bf16 v[78:81], v[158:161], v[214:217], v[78:81]
	v_mfma_f32_16x16x32_bf16 v[74:77], v[166:169], v[214:217], v[74:77]
	v_mfma_f32_16x16x32_bf16 v[118:121], v[170:173], v[186:189], v[118:121]
	v_mfma_f32_16x16x32_bf16 v[114:117], v[178:181], v[186:189], v[114:117]
	v_mfma_f32_16x16x32_bf16 v[102:105], v[170:173], v[194:197], v[102:105]
	v_mfma_f32_16x16x32_bf16 v[98:101], v[178:181], v[194:197], v[98:101]
	v_mfma_f32_16x16x32_bf16 v[86:89], v[170:173], v[202:205], v[86:89]
	v_mfma_f32_16x16x32_bf16 v[82:85], v[178:181], v[202:205], v[82:85]
	v_mfma_f32_16x16x32_bf16 v[70:73], v[170:173], v[210:213], v[70:73]
	v_mfma_f32_16x16x32_bf16 v[66:69], v[178:181], v[210:213], v[66:69]
	v_mfma_f32_16x16x32_bf16 v[118:121], v[174:177], v[190:193], v[118:121]
	v_mfma_f32_16x16x32_bf16 v[114:117], v[182:185], v[190:193], v[114:117]
	v_mfma_f32_16x16x32_bf16 v[102:105], v[174:177], v[198:201], v[102:105]
	v_mfma_f32_16x16x32_bf16 v[98:101], v[182:185], v[198:201], v[98:101]
	v_mfma_f32_16x16x32_bf16 v[86:89], v[174:177], v[206:209], v[86:89]
	v_mfma_f32_16x16x32_bf16 v[82:85], v[182:185], v[206:209], v[82:85]
	v_mfma_f32_16x16x32_bf16 v[70:73], v[174:177], v[214:217], v[70:73]
	v_mfma_f32_16x16x32_bf16 v[66:69], v[182:185], v[214:217], v[66:69]
	s_barrier
	s_add_i32 s18, s20, s35
	v_lshl_add_u64 v[218:219], v[218:219], 0, s[40:41]
	s_mov_b32 m0, s18
	ds_read_b128 v[186:189], v156 offset:49152
	ds_read_b128 v[190:193], v156 offset:50176
	ds_read_b128 v[194:197], v156 offset:51200
	ds_read_b128 v[198:201], v156 offset:52224
	ds_read_b128 v[202:205], v156 offset:53248
	ds_read_b128 v[206:209], v156 offset:54272
	ds_read_b128 v[210:213], v156 offset:55296
	ds_read_b128 v[214:217], v156 offset:56320
	global_load_lds_dwordx4 v[218:219], off
	s_add_i32 m0, s18, 0x2000
	s_add_u32 s18, s86, 0x100080
	v_lshl_add_u64 v[218:219], v[220:221], 0, s[40:41]
	s_addc_u32 s19, s87, 0
	s_add_i32 s20, s21, s35
	global_load_lds_dwordx4 v[218:219], off
	v_lshl_add_u64 v[218:219], s[18:19], 0, v[132:133]
	s_mov_b32 m0, s20
	s_nop 0
	global_load_lds_dwordx4 v[218:219], off
	v_lshl_add_u64 v[218:219], s[18:19], 0, v[136:137]
	s_add_i32 m0, s20, 0x2000
	s_nop 0
	global_load_lds_dwordx4 v[218:219], off
	v_lshl_add_u64 v[218:219], v[222:223], 0, s[40:41]
	s_mov_b32 m0, s66
	s_nop 0
	global_load_lds_dwordx4 v[218:219], off
	v_lshl_add_u64 v[218:219], v[224:225], 0, s[40:41]
	s_mov_b32 m0, s67
	s_nop 0
	global_load_lds_dwordx4 v[218:219], off
	s_waitcnt vmcnt(8)
	s_waitcnt lgkmcnt(0)
	s_barrier
	s_waitcnt lgkmcnt(0)
	v_mfma_f32_16x16x32_bf16 v[62:65], v[146:149], v[186:189], v[62:65]
	v_mfma_f32_16x16x32_bf16 v[58:61], v[162:165], v[186:189], v[58:61]
	v_mfma_f32_16x16x32_bf16 v[46:49], v[146:149], v[194:197], v[46:49]
	v_mfma_f32_16x16x32_bf16 v[42:45], v[162:165], v[194:197], v[42:45]
	v_mfma_f32_16x16x32_bf16 v[30:33], v[146:149], v[202:205], v[30:33]
	v_mfma_f32_16x16x32_bf16 v[26:29], v[162:165], v[202:205], v[26:29]
	v_mfma_f32_16x16x32_bf16 v[14:17], v[146:149], v[210:213], v[14:17]
	v_mfma_f32_16x16x32_bf16 v[10:13], v[162:165], v[210:213], v[10:13]
	v_mfma_f32_16x16x32_bf16 v[62:65], v[158:161], v[190:193], v[62:65]
	v_mfma_f32_16x16x32_bf16 v[58:61], v[166:169], v[190:193], v[58:61]
	v_mfma_f32_16x16x32_bf16 v[46:49], v[158:161], v[198:201], v[46:49]
	v_mfma_f32_16x16x32_bf16 v[42:45], v[166:169], v[198:201], v[42:45]
	v_mfma_f32_16x16x32_bf16 v[30:33], v[158:161], v[206:209], v[30:33]
	v_mfma_f32_16x16x32_bf16 v[26:29], v[166:169], v[206:209], v[26:29]
	v_mfma_f32_16x16x32_bf16 v[14:17], v[158:161], v[214:217], v[14:17]
	v_mfma_f32_16x16x32_bf16 v[10:13], v[166:169], v[214:217], v[10:13]
	v_mfma_f32_16x16x32_bf16 v[54:57], v[170:173], v[186:189], v[54:57]
	v_mfma_f32_16x16x32_bf16 v[50:53], v[178:181], v[186:189], v[50:53]
	v_mfma_f32_16x16x32_bf16 v[38:41], v[170:173], v[194:197], v[38:41]
	v_mfma_f32_16x16x32_bf16 v[34:37], v[178:181], v[194:197], v[34:37]
	v_mfma_f32_16x16x32_bf16 v[22:25], v[170:173], v[202:205], v[22:25]
	v_mfma_f32_16x16x32_bf16 v[18:21], v[178:181], v[202:205], v[18:21]
	v_mfma_f32_16x16x32_bf16 v[6:9], v[170:173], v[210:213], v[6:9]
	v_mfma_f32_16x16x32_bf16 v[2:5], v[178:181], v[210:213], v[2:5]
	v_mfma_f32_16x16x32_bf16 v[54:57], v[174:177], v[190:193], v[54:57]
	v_mfma_f32_16x16x32_bf16 v[50:53], v[182:185], v[190:193], v[50:53]
	v_mfma_f32_16x16x32_bf16 v[38:41], v[174:177], v[198:201], v[38:41]
	v_mfma_f32_16x16x32_bf16 v[34:37], v[182:185], v[198:201], v[34:37]
	v_mfma_f32_16x16x32_bf16 v[22:25], v[174:177], v[206:209], v[22:25]
	v_mfma_f32_16x16x32_bf16 v[18:21], v[182:185], v[206:209], v[18:21]
	v_mfma_f32_16x16x32_bf16 v[6:9], v[174:177], v[214:217], v[6:9]
	v_mfma_f32_16x16x32_bf16 v[2:5], v[182:185], v[214:217], v[2:5]
	s_barrier
	s_add_i32 s17, s17, 2
	s_add_u32 s84, s84, 0x100
	s_addc_u32 s85, s85, 0
	s_add_u32 s13, s13, 0x100
	s_addc_u32 s16, s16, 0
	s_cmp_gt_u32 s17, 61
	s_cbranch_scc0 .LBB0_541
	s_setprio 0
	s_and_b64 vcc, exec, s[42:43]
	s_cbranch_vccz .LBB0_544
	s_barrier

.LBB0_885:
	s_ashr_i32 s41, s40, 31
	s_lshl_b64 s[8:9], s[40:41], 21
	s_add_u32 s42, s30, s8
	s_addc_u32 s43, s31, s9
	s_and_b64 s[8:9], s[2:3], exec
	s_cselect_b32 s8, s43, s49
	s_cselect_b32 s9, s42, s48
	s_ashr_i32 s29, s28, 31
	s_lshl_b64 s[12:13], s[28:29], 21
	s_add_u32 s44, s72, s12
	s_addc_u32 s45, s73, s13
	s_and_b64 s[12:13], s[2:3], exec
	s_cselect_b32 s12, s45, s51
	s_cselect_b32 s13, s44, s50
	s_add_u32 s48, s48, 0x100080
	s_addc_u32 s49, s49, 0
	s_add_u32 s29, s50, 0x100
	v_mov_b32_e32 v2, 0
	s_addc_u32 s41, s51, 0
	s_mov_b32 s78, -2
	v_mov_b32_e32 v3, v2
	v_mov_b32_e32 v4, v2
	v_mov_b32_e32 v5, v2
	v_mov_b32_e32 v6, v2
	v_mov_b32_e32 v7, v2
	v_mov_b32_e32 v8, v2
	v_mov_b32_e32 v9, v2
	v_mov_b32_e32 v10, v2
	v_mov_b32_e32 v11, v2
	v_mov_b32_e32 v12, v2
	v_mov_b32_e32 v13, v2
	v_mov_b32_e32 v18, v2
	v_mov_b32_e32 v19, v2
	v_mov_b32_e32 v20, v2
	v_mov_b32_e32 v21, v2
	v_mov_b32_e32 v26, v2
	v_mov_b32_e32 v27, v2
	v_mov_b32_e32 v28, v2
	v_mov_b32_e32 v29, v2
	v_mov_b32_e32 v34, v2
	v_mov_b32_e32 v35, v2
	v_mov_b32_e32 v36, v2
	v_mov_b32_e32 v37, v2
	v_mov_b32_e32 v42, v2
	v_mov_b32_e32 v43, v2
	v_mov_b32_e32 v44, v2
	v_mov_b32_e32 v45, v2
	v_mov_b32_e32 v50, v2
	v_mov_b32_e32 v51, v2
	v_mov_b32_e32 v52, v2
	v_mov_b32_e32 v53, v2
	v_mov_b32_e32 v14, v2
	v_mov_b32_e32 v15, v2
	v_mov_b32_e32 v16, v2
	v_mov_b32_e32 v17, v2
	v_mov_b32_e32 v22, v2
	v_mov_b32_e32 v23, v2
	v_mov_b32_e32 v24, v2
	v_mov_b32_e32 v25, v2
	v_mov_b32_e32 v30, v2
	v_mov_b32_e32 v31, v2
	v_mov_b32_e32 v32, v2
	v_mov_b32_e32 v33, v2
	v_mov_b32_e32 v38, v2
	v_mov_b32_e32 v39, v2
	v_mov_b32_e32 v40, v2
	v_mov_b32_e32 v41, v2
	v_mov_b32_e32 v46, v2
	v_mov_b32_e32 v47, v2
	v_mov_b32_e32 v48, v2
	v_mov_b32_e32 v49, v2
	v_mov_b32_e32 v54, v2
	v_mov_b32_e32 v55, v2
	v_mov_b32_e32 v56, v2
	v_mov_b32_e32 v57, v2
	v_mov_b32_e32 v58, v2
	v_mov_b32_e32 v59, v2
	v_mov_b32_e32 v60, v2
	v_mov_b32_e32 v61, v2
	v_mov_b32_e32 v62, v2
	v_mov_b32_e32 v63, v2
	v_mov_b32_e32 v64, v2
	v_mov_b32_e32 v65, v2
	v_mov_b32_e32 v66, v2
	v_mov_b32_e32 v67, v2
	v_mov_b32_e32 v68, v2
	v_mov_b32_e32 v69, v2
	v_mov_b32_e32 v70, v2
	v_mov_b32_e32 v71, v2
	v_mov_b32_e32 v72, v2
	v_mov_b32_e32 v73, v2
	v_mov_b32_e32 v74, v2
	v_mov_b32_e32 v75, v2
	v_mov_b32_e32 v76, v2
	v_mov_b32_e32 v77, v2
	v_mov_b32_e32 v82, v2
	v_mov_b32_e32 v83, v2
	v_mov_b32_e32 v84, v2
	v_mov_b32_e32 v85, v2
	v_mov_b32_e32 v90, v2
	v_mov_b32_e32 v91, v2
	v_mov_b32_e32 v92, v2
	v_mov_b32_e32 v93, v2
	v_mov_b32_e32 v98, v2
	v_mov_b32_e32 v99, v2
	v_mov_b32_e32 v100, v2
	v_mov_b32_e32 v101, v2
	v_mov_b32_e32 v106, v2
	v_mov_b32_e32 v107, v2
	v_mov_b32_e32 v108, v2
	v_mov_b32_e32 v109, v2
	v_mov_b32_e32 v114, v2
	v_mov_b32_e32 v115, v2
	v_mov_b32_e32 v116, v2
	v_mov_b32_e32 v117, v2
	v_mov_b32_e32 v78, v2
	v_mov_b32_e32 v79, v2
	v_mov_b32_e32 v80, v2
	v_mov_b32_e32 v81, v2
	v_mov_b32_e32 v86, v2
	v_mov_b32_e32 v87, v2
	v_mov_b32_e32 v88, v2
	v_mov_b32_e32 v89, v2
	v_mov_b32_e32 v94, v2
	v_mov_b32_e32 v95, v2
	v_mov_b32_e32 v96, v2
	v_mov_b32_e32 v97, v2
	v_mov_b32_e32 v102, v2
	v_mov_b32_e32 v103, v2
	v_mov_b32_e32 v104, v2
	v_mov_b32_e32 v105, v2
	v_mov_b32_e32 v110, v2
	v_mov_b32_e32 v111, v2
	v_mov_b32_e32 v112, v2
	v_mov_b32_e32 v113, v2
	v_mov_b32_e32 v118, v2
	v_mov_b32_e32 v119, v2
	v_mov_b32_e32 v120, v2
	v_mov_b32_e32 v121, v2
	v_mov_b32_e32 v122, v2
	v_mov_b32_e32 v123, v2
	v_mov_b32_e32 v124, v2
	v_mov_b32_e32 v125, v2
	v_mov_b32_e32 v126, v2
	v_mov_b32_e32 v127, v2
	v_mov_b32_e32 v128, v2
	v_mov_b32_e32 v129, v2
	s_and_b64 vcc, exec, s[18:19]
	s_cbranch_vccnz .Lsp_p9
	s_setprio 1
.Lsp_p9:
.LBB0_886:
	ds_read_b128 v[154:157], v150
	ds_read_b128 v[158:161], v150 offset:1024
	ds_read_b128 v[162:165], v150 offset:2048
	ds_read_b128 v[166:169], v150 offset:3072
	ds_read_b128 v[170:173], v151
	ds_read_b128 v[174:177], v151 offset:1024
	ds_read_b128 v[178:181], v151 offset:2048
	ds_read_b128 v[182:185], v151 offset:3072
	s_add_u32 s50, s48, 0xfff00080
	s_addc_u32 s51, s49, -1
	s_cmp_eq_u32 s78, 60
	s_cselect_b32 s53, s8, s51
	s_cselect_b32 s52, s9, s50
	s_cselect_b32 s51, s12, s41
	s_cselect_b32 s50, s13, s29
	v_lshl_add_u64 v[146:147], s[48:49], 0, v[138:139]
	s_add_i32 m0, s47, 0xc000
	ds_read_b128 v[186:189], v152
	ds_read_b128 v[190:193], v152 offset:1024
	ds_read_b128 v[194:197], v152 offset:2048
	ds_read_b128 v[198:201], v152 offset:3072
	ds_read_b128 v[202:205], v152 offset:4096
	ds_read_b128 v[206:209], v152 offset:5120
	ds_read_b128 v[210:213], v152 offset:6144
	ds_read_b128 v[214:217], v152 offset:7168
	global_load_lds_dwordx4 v[146:147], off
	v_lshl_add_u64 v[146:147], s[48:49], 0, v[140:141]
	s_add_i32 m0, s47, 0xe000
	s_nop 0
	global_load_lds_dwordx4 v[146:147], off
	s_waitcnt vmcnt(8)
	s_waitcnt lgkmcnt(0)
	s_barrier
	s_waitcnt lgkmcnt(0)
	v_mfma_f32_16x16x32_bf16 v[126:129], v[154:157], v[186:189], v[126:129]
	v_mfma_f32_16x16x32_bf16 v[122:125], v[162:165], v[186:189], v[122:125]
	v_mfma_f32_16x16x32_bf16 v[118:121], v[154:157], v[194:197], v[118:121]
	v_mfma_f32_16x16x32_bf16 v[110:113], v[162:165], v[194:197], v[110:113]
	v_mfma_f32_16x16x32_bf16 v[102:105], v[154:157], v[202:205], v[102:105]
	v_mfma_f32_16x16x32_bf16 v[94:97], v[162:165], v[202:205], v[94:97]
	v_mfma_f32_16x16x32_bf16 v[86:89], v[154:157], v[210:213], v[86:89]
	v_mfma_f32_16x16x32_bf16 v[78:81], v[162:165], v[210:213], v[78:81]
	v_mfma_f32_16x16x32_bf16 v[126:129], v[158:161], v[190:193], v[126:129]
	v_mfma_f32_16x16x32_bf16 v[122:125], v[166:169], v[190:193], v[122:125]
	v_mfma_f32_16x16x32_bf16 v[118:121], v[158:161], v[198:201], v[118:121]
	v_mfma_f32_16x16x32_bf16 v[110:113], v[166:169], v[198:201], v[110:113]
	v_mfma_f32_16x16x32_bf16 v[102:105], v[158:161], v[206:209], v[102:105]
	v_mfma_f32_16x16x32_bf16 v[94:97], v[166:169], v[206:209], v[94:97]
	v_mfma_f32_16x16x32_bf16 v[86:89], v[158:161], v[214:217], v[86:89]
	v_mfma_f32_16x16x32_bf16 v[78:81], v[166:169], v[214:217], v[78:81]
	v_mfma_f32_16x16x32_bf16 v[114:117], v[170:173], v[186:189], v[114:117]
	v_mfma_f32_16x16x32_bf16 v[106:109], v[178:181], v[186:189], v[106:109]
	v_mfma_f32_16x16x32_bf16 v[98:101], v[170:173], v[194:197], v[98:101]
	v_mfma_f32_16x16x32_bf16 v[90:93], v[178:181], v[194:197], v[90:93]
	v_mfma_f32_16x16x32_bf16 v[82:85], v[170:173], v[202:205], v[82:85]
	v_mfma_f32_16x16x32_bf16 v[74:77], v[178:181], v[202:205], v[74:77]
	v_mfma_f32_16x16x32_bf16 v[70:73], v[170:173], v[210:213], v[70:73]
	v_mfma_f32_16x16x32_bf16 v[66:69], v[178:181], v[210:213], v[66:69]
	v_mfma_f32_16x16x32_bf16 v[114:117], v[174:177], v[190:193], v[114:117]
	v_mfma_f32_16x16x32_bf16 v[106:109], v[182:185], v[190:193], v[106:109]
	v_mfma_f32_16x16x32_bf16 v[98:101], v[174:177], v[198:201], v[98:101]
	v_mfma_f32_16x16x32_bf16 v[90:93], v[182:185], v[198:201], v[90:93]
	v_mfma_f32_16x16x32_bf16 v[82:85], v[174:177], v[206:209], v[82:85]
	v_mfma_f32_16x16x32_bf16 v[74:77], v[182:185], v[206:209], v[74:77]
	v_mfma_f32_16x16x32_bf16 v[70:73], v[174:177], v[214:217], v[70:73]
	v_mfma_f32_16x16x32_bf16 v[66:69], v[182:185], v[214:217], v[66:69]
	s_barrier
	s_add_i32 s79, s67, s54
	v_lshl_add_u64 v[146:147], s[50:51], 0, v[132:133]
	s_mov_b32 m0, s79
	ds_read_b128 v[186:189], v152 offset:16384
	ds_read_b128 v[190:193], v152 offset:17408
	ds_read_b128 v[194:197], v152 offset:18432
	ds_read_b128 v[198:201], v152 offset:19456
	ds_read_b128 v[202:205], v152 offset:20480
	ds_read_b128 v[206:209], v152 offset:21504
	ds_read_b128 v[210:213], v152 offset:22528
	ds_read_b128 v[214:217], v152 offset:23552
	global_load_lds_dwordx4 v[146:147], off
	s_add_i32 m0, s79, 0x2000
	s_add_u32 s80, s50, 0x100000
	v_lshl_add_u64 v[218:219], s[50:51], 0, v[136:137]
	s_addc_u32 s81, s51, 0
	s_add_i32 s79, s68, s54
	global_load_lds_dwordx4 v[218:219], off
	v_lshl_add_u64 v[220:221], s[80:81], 0, v[132:133]
	s_mov_b32 m0, s79
	v_lshl_add_u64 v[222:223], s[52:53], 0, v[134:135]
	global_load_lds_dwordx4 v[220:221], off
	v_lshl_add_u64 v[220:221], s[80:81], 0, v[136:137]
	s_add_i32 m0, s79, 0x2000
	s_nop 0
	global_load_lds_dwordx4 v[220:221], off
	v_lshl_add_u64 v[220:221], s[52:53], 0, v[130:131]
	s_mov_b32 m0, s47
	s_nop 0
	global_load_lds_dwordx4 v[220:221], off
	s_mov_b32 m0, s55
	s_nop 0
	global_load_lds_dwordx4 v[222:223], off
	s_waitcnt vmcnt(8)
	s_waitcnt lgkmcnt(0)
	s_barrier
	s_waitcnt lgkmcnt(0)
	v_mfma_f32_16x16x32_bf16 v[62:65], v[154:157], v[186:189], v[62:65]
	v_mfma_f32_16x16x32_bf16 v[58:61], v[162:165], v[186:189], v[58:61]
	v_mfma_f32_16x16x32_bf16 v[54:57], v[154:157], v[194:197], v[54:57]
	v_mfma_f32_16x16x32_bf16 v[46:49], v[162:165], v[194:197], v[46:49]
	v_mfma_f32_16x16x32_bf16 v[38:41], v[154:157], v[202:205], v[38:41]
	v_mfma_f32_16x16x32_bf16 v[30:33], v[162:165], v[202:205], v[30:33]
	v_mfma_f32_16x16x32_bf16 v[22:25], v[154:157], v[210:213], v[22:25]
	v_mfma_f32_16x16x32_bf16 v[14:17], v[162:165], v[210:213], v[14:17]
	v_mfma_f32_16x16x32_bf16 v[62:65], v[158:161], v[190:193], v[62:65]
	v_mfma_f32_16x16x32_bf16 v[58:61], v[166:169], v[190:193], v[58:61]
	v_mfma_f32_16x16x32_bf16 v[54:57], v[158:161], v[198:201], v[54:57]
	v_mfma_f32_16x16x32_bf16 v[46:49], v[166:169], v[198:201], v[46:49]
	v_mfma_f32_16x16x32_bf16 v[38:41], v[158:161], v[206:209], v[38:41]
	v_mfma_f32_16x16x32_bf16 v[30:33], v[166:169], v[206:209], v[30:33]
	v_mfma_f32_16x16x32_bf16 v[22:25], v[158:161], v[214:217], v[22:25]
	v_mfma_f32_16x16x32_bf16 v[14:17], v[166:169], v[214:217], v[14:17]
	v_mfma_f32_16x16x32_bf16 v[50:53], v[170:173], v[186:189], v[50:53]
	v_mfma_f32_16x16x32_bf16 v[42:45], v[178:181], v[186:189], v[42:45]
	v_mfma_f32_16x16x32_bf16 v[34:37], v[170:173], v[194:197], v[34:37]
	v_mfma_f32_16x16x32_bf16 v[26:29], v[178:181], v[194:197], v[26:29]
	v_mfma_f32_16x16x32_bf16 v[18:21], v[170:173], v[202:205], v[18:21]
	v_mfma_f32_16x16x32_bf16 v[10:13], v[178:181], v[202:205], v[10:13]
	v_mfma_f32_16x16x32_bf16 v[6:9], v[170:173], v[210:213], v[6:9]
	v_mfma_f32_16x16x32_bf16 v[2:5], v[178:181], v[210:213], v[2:5]
	v_mfma_f32_16x16x32_bf16 v[50:53], v[174:177], v[190:193], v[50:53]
	v_mfma_f32_16x16x32_bf16 v[42:45], v[182:185], v[190:193], v[42:45]
	v_mfma_f32_16x16x32_bf16 v[34:37], v[174:177], v[198:201], v[34:37]
	v_mfma_f32_16x16x32_bf16 v[26:29], v[182:185], v[198:201], v[26:29]
	v_mfma_f32_16x16x32_bf16 v[18:21], v[174:177], v[206:209], v[18:21]
	v_mfma_f32_16x16x32_bf16 v[10:13], v[182:185], v[206:209], v[10:13]
	v_mfma_f32_16x16x32_bf16 v[6:9], v[174:177], v[214:217], v[6:9]
	v_mfma_f32_16x16x32_bf16 v[2:5], v[182:185], v[214:217], v[2:5]
	s_barrier
	s_add_i32 s79, 0, 0x18000
	v_add_u32_e32 v153, s79, v148
	s_add_i32 s80, 0, 0x1c000
	ds_read_b128 v[154:157], v153
	ds_read_b128 v[158:161], v153 offset:1024
	ds_read_b128 v[162:165], v153 offset:2048
	ds_read_b128 v[166:169], v153 offset:3072
	v_add_u32_e32 v153, s80, v148
	ds_read_b128 v[170:173], v153
	ds_read_b128 v[174:177], v153 offset:1024
	ds_read_b128 v[178:181], v153 offset:2048
	ds_read_b128 v[182:185], v153 offset:3072
	s_add_u32 s52, s52, 0x100000
	s_addc_u32 s53, s53, 0
	s_mov_b32 m0, s56
	v_lshl_add_u64 v[224:225], s[52:53], 0, v[130:131]
	ds_read_b128 v[186:189], v152 offset:32768
	ds_read_b128 v[190:193], v152 offset:33792
	ds_read_b128 v[194:197], v152 offset:34816
	ds_read_b128 v[198:201], v152 offset:35840
	ds_read_b128 v[202:205], v152 offset:36864
	ds_read_b128 v[206:209], v152 offset:37888
	ds_read_b128 v[210:213], v152 offset:38912
	ds_read_b128 v[214:217], v152 offset:39936
	global_load_lds_dwordx4 v[224:225], off
	v_lshl_add_u64 v[224:225], s[52:53], 0, v[134:135]
	s_mov_b32 m0, s57
	s_nop 0
	global_load_lds_dwordx4 v[224:225], off
	s_waitcnt vmcnt(8)
	s_waitcnt lgkmcnt(0)
	s_barrier
	s_waitcnt lgkmcnt(0)
	v_mfma_f32_16x16x32_bf16 v[126:129], v[154:157], v[186:189], v[126:129]
	v_mfma_f32_16x16x32_bf16 v[122:125], v[162:165], v[186:189], v[122:125]
	v_mfma_f32_16x16x32_bf16 v[118:121], v[154:157], v[194:197], v[118:121]
	v_mfma_f32_16x16x32_bf16 v[110:113], v[162:165], v[194:197], v[110:113]
	v_mfma_f32_16x16x32_bf16 v[102:105], v[154:157], v[202:205], v[102:105]
	v_mfma_f32_16x16x32_bf16 v[94:97], v[162:165], v[202:205], v[94:97]
	v_mfma_f32_16x16x32_bf16 v[86:89], v[154:157], v[210:213], v[86:89]
	v_mfma_f32_16x16x32_bf16 v[78:81], v[162:165], v[210:213], v[78:81]
	v_mfma_f32_16x16x32_bf16 v[126:129], v[158:161], v[190:193], v[126:129]
	v_mfma_f32_16x16x32_bf16 v[122:125], v[166:169], v[190:193], v[122:125]
	v_mfma_f32_16x16x32_bf16 v[118:121], v[158:161], v[198:201], v[118:121]
	v_mfma_f32_16x16x32_bf16 v[110:113], v[166:169], v[198:201], v[110:113]
	v_mfma_f32_16x16x32_bf16 v[102:105], v[158:161], v[206:209], v[102:105]
	v_mfma_f32_16x16x32_bf16 v[94:97], v[166:169], v[206:209], v[94:97]
	v_mfma_f32_16x16x32_bf16 v[86:89], v[158:161], v[214:217], v[86:89]
	v_mfma_f32_16x16x32_bf16 v[78:81], v[166:169], v[214:217], v[78:81]
	v_mfma_f32_16x16x32_bf16 v[114:117], v[170:173], v[186:189], v[114:117]
	v_mfma_f32_16x16x32_bf16 v[106:109], v[178:181], v[186:189], v[106:109]
	v_mfma_f32_16x16x32_bf16 v[98:101], v[170:173], v[194:197], v[98:101]
	v_mfma_f32_16x16x32_bf16 v[90:93], v[178:181], v[194:197], v[90:93]
	v_mfma_f32_16x16x32_bf16 v[82:85], v[170:173], v[202:205], v[82:85]
	v_mfma_f32_16x16x32_bf16 v[74:77], v[178:181], v[202:205], v[74:77]
	v_mfma_f32_16x16x32_bf16 v[70:73], v[170:173], v[210:213], v[70:73]
	v_mfma_f32_16x16x32_bf16 v[66:69], v[178:181], v[210:213], v[66:69]
	v_mfma_f32_16x16x32_bf16 v[114:117], v[174:177], v[190:193], v[114:117]
	v_mfma_f32_16x16x32_bf16 v[106:109], v[182:185], v[190:193], v[106:109]
	v_mfma_f32_16x16x32_bf16 v[98:101], v[174:177], v[198:201], v[98:101]
	v_mfma_f32_16x16x32_bf16 v[90:93], v[182:185], v[198:201], v[90:93]
	v_mfma_f32_16x16x32_bf16 v[82:85], v[174:177], v[206:209], v[82:85]
	v_mfma_f32_16x16x32_bf16 v[74:77], v[182:185], v[206:209], v[74:77]
	v_mfma_f32_16x16x32_bf16 v[70:73], v[174:177], v[214:217], v[70:73]
	v_mfma_f32_16x16x32_bf16 v[66:69], v[182:185], v[214:217], v[66:69]
	s_barrier
	s_add_i32 s52, s79, s54
	v_lshl_add_u64 v[146:147], v[146:147], 0, s[16:17]
	s_mov_b32 m0, s52
	ds_read_b128 v[186:189], v152 offset:49152
	ds_read_b128 v[190:193], v152 offset:50176
	ds_read_b128 v[194:197], v152 offset:51200
	ds_read_b128 v[198:201], v152 offset:52224
	ds_read_b128 v[202:205], v152 offset:53248
	ds_read_b128 v[206:209], v152 offset:54272
	ds_read_b128 v[210:213], v152 offset:55296
	ds_read_b128 v[214:217], v152 offset:56320
	global_load_lds_dwordx4 v[146:147], off
	s_add_i32 m0, s52, 0x2000
	s_add_u32 s50, s50, 0x100080
	v_lshl_add_u64 v[146:147], v[218:219], 0, s[16:17]
	s_addc_u32 s51, s51, 0
	s_add_i32 s52, s80, s54
	global_load_lds_dwordx4 v[146:147], off
	v_lshl_add_u64 v[146:147], s[50:51], 0, v[132:133]
	s_mov_b32 m0, s52
	s_nop 0
	global_load_lds_dwordx4 v[146:147], off
	v_lshl_add_u64 v[146:147], s[50:51], 0, v[136:137]
	s_add_i32 m0, s52, 0x2000
	s_nop 0
	global_load_lds_dwordx4 v[146:147], off
	v_lshl_add_u64 v[146:147], v[220:221], 0, s[16:17]
	s_mov_b32 m0, s59
	s_nop 0
	global_load_lds_dwordx4 v[146:147], off
	v_lshl_add_u64 v[146:147], v[222:223], 0, s[16:17]
	s_mov_b32 m0, s61
	s_nop 0
	global_load_lds_dwordx4 v[146:147], off
	s_waitcnt vmcnt(8)
	s_waitcnt lgkmcnt(0)
	s_barrier
	s_waitcnt lgkmcnt(0)
	v_mfma_f32_16x16x32_bf16 v[62:65], v[154:157], v[186:189], v[62:65]
	v_mfma_f32_16x16x32_bf16 v[58:61], v[162:165], v[186:189], v[58:61]
	v_mfma_f32_16x16x32_bf16 v[54:57], v[154:157], v[194:197], v[54:57]
	v_mfma_f32_16x16x32_bf16 v[46:49], v[162:165], v[194:197], v[46:49]
	v_mfma_f32_16x16x32_bf16 v[38:41], v[154:157], v[202:205], v[38:41]
	v_mfma_f32_16x16x32_bf16 v[30:33], v[162:165], v[202:205], v[30:33]
	v_mfma_f32_16x16x32_bf16 v[22:25], v[154:157], v[210:213], v[22:25]
	v_mfma_f32_16x16x32_bf16 v[14:17], v[162:165], v[210:213], v[14:17]
	v_mfma_f32_16x16x32_bf16 v[62:65], v[158:161], v[190:193], v[62:65]
	v_mfma_f32_16x16x32_bf16 v[58:61], v[166:169], v[190:193], v[58:61]
	v_mfma_f32_16x16x32_bf16 v[54:57], v[158:161], v[198:201], v[54:57]
	v_mfma_f32_16x16x32_bf16 v[46:49], v[166:169], v[198:201], v[46:49]
	v_mfma_f32_16x16x32_bf16 v[38:41], v[158:161], v[206:209], v[38:41]
	v_mfma_f32_16x16x32_bf16 v[30:33], v[166:169], v[206:209], v[30:33]
	v_mfma_f32_16x16x32_bf16 v[22:25], v[158:161], v[214:217], v[22:25]
	v_mfma_f32_16x16x32_bf16 v[14:17], v[166:169], v[214:217], v[14:17]
	v_mfma_f32_16x16x32_bf16 v[50:53], v[170:173], v[186:189], v[50:53]
	v_mfma_f32_16x16x32_bf16 v[42:45], v[178:181], v[186:189], v[42:45]
	v_mfma_f32_16x16x32_bf16 v[34:37], v[170:173], v[194:197], v[34:37]
	v_mfma_f32_16x16x32_bf16 v[26:29], v[178:181], v[194:197], v[26:29]
	v_mfma_f32_16x16x32_bf16 v[18:21], v[170:173], v[202:205], v[18:21]
	v_mfma_f32_16x16x32_bf16 v[10:13], v[178:181], v[202:205], v[10:13]
	v_mfma_f32_16x16x32_bf16 v[6:9], v[170:173], v[210:213], v[6:9]
	v_mfma_f32_16x16x32_bf16 v[2:5], v[178:181], v[210:213], v[2:5]
	v_mfma_f32_16x16x32_bf16 v[50:53], v[174:177], v[190:193], v[50:53]
	v_mfma_f32_16x16x32_bf16 v[42:45], v[182:185], v[190:193], v[42:45]
	v_mfma_f32_16x16x32_bf16 v[34:37], v[174:177], v[198:201], v[34:37]
	v_mfma_f32_16x16x32_bf16 v[26:29], v[182:185], v[198:201], v[26:29]
	v_mfma_f32_16x16x32_bf16 v[18:21], v[174:177], v[206:209], v[18:21]
	v_mfma_f32_16x16x32_bf16 v[10:13], v[182:185], v[206:209], v[10:13]
	v_mfma_f32_16x16x32_bf16 v[6:9], v[174:177], v[214:217], v[6:9]
	v_mfma_f32_16x16x32_bf16 v[2:5], v[182:185], v[214:217], v[2:5]
	s_barrier
	s_add_i32 s78, s78, 2
	s_add_u32 s48, s48, 0x100
	s_addc_u32 s49, s49, 0
	s_add_u32 s29, s29, 0x100
	s_addc_u32 s41, s41, 0
	s_cmp_gt_u32 s78, 61
	s_cbranch_scc0 .LBB0_886
	s_setprio 0
	s_and_b64 vcc, exec, s[18:19]
	s_cbranch_vccz .LBB0_889
	s_barrier

.LBB0_1014:
	s_ashr_i32 s23, s22, 31
	s_lshl_b64 s[8:9], s[22:23], 20
	s_add_u32 s24, s30, s8
	s_addc_u32 s25, s31, s9
	s_and_b64 s[8:9], s[2:3], exec
	s_cselect_b32 s8, s25, s43
	s_cselect_b32 s9, s24, s42
	s_ashr_i32 s21, s20, 31
	s_lshl_b64 s[28:29], s[20:21], 20
	s_add_u32 s28, s14, s28
	s_addc_u32 s29, s15, s29
	s_and_b64 s[46:47], s[2:3], exec
	s_cselect_b32 s21, s29, s45
	s_cselect_b32 s23, s28, s44
	s_add_u32 s42, s42, 0x80080
	s_addc_u32 s43, s43, 0
	s_add_u32 s61, s44, 0x100
	v_mov_b32_e32 v2, 0
	s_addc_u32 s66, s45, 0
	s_mov_b32 s67, -2
	v_mov_b32_e32 v3, v2
	v_mov_b32_e32 v4, v2
	v_mov_b32_e32 v5, v2
	v_mov_b32_e32 v6, v2
	v_mov_b32_e32 v7, v2
	v_mov_b32_e32 v8, v2
	v_mov_b32_e32 v9, v2
	v_mov_b32_e32 v18, v2
	v_mov_b32_e32 v19, v2
	v_mov_b32_e32 v20, v2
	v_mov_b32_e32 v21, v2
	v_mov_b32_e32 v22, v2
	v_mov_b32_e32 v23, v2
	v_mov_b32_e32 v24, v2
	v_mov_b32_e32 v25, v2
	v_mov_b32_e32 v34, v2
	v_mov_b32_e32 v35, v2
	v_mov_b32_e32 v36, v2
	v_mov_b32_e32 v37, v2
	v_mov_b32_e32 v38, v2
	v_mov_b32_e32 v39, v2
	v_mov_b32_e32 v40, v2
	v_mov_b32_e32 v41, v2
	v_mov_b32_e32 v50, v2
	v_mov_b32_e32 v51, v2
	v_mov_b32_e32 v52, v2
	v_mov_b32_e32 v53, v2
	v_mov_b32_e32 v54, v2
	v_mov_b32_e32 v55, v2
	v_mov_b32_e32 v56, v2
	v_mov_b32_e32 v57, v2
	v_mov_b32_e32 v10, v2
	v_mov_b32_e32 v11, v2
	v_mov_b32_e32 v12, v2
	v_mov_b32_e32 v13, v2
	v_mov_b32_e32 v14, v2
	v_mov_b32_e32 v15, v2
	v_mov_b32_e32 v16, v2
	v_mov_b32_e32 v17, v2
	v_mov_b32_e32 v26, v2
	v_mov_b32_e32 v27, v2
	v_mov_b32_e32 v28, v2
	v_mov_b32_e32 v29, v2
	v_mov_b32_e32 v30, v2
	v_mov_b32_e32 v31, v2
	v_mov_b32_e32 v32, v2
	v_mov_b32_e32 v33, v2
	v_mov_b32_e32 v42, v2
	v_mov_b32_e32 v43, v2
	v_mov_b32_e32 v44, v2
	v_mov_b32_e32 v45, v2
	v_mov_b32_e32 v46, v2
	v_mov_b32_e32 v47, v2
	v_mov_b32_e32 v48, v2
	v_mov_b32_e32 v49, v2
	v_mov_b32_e32 v58, v2
	v_mov_b32_e32 v59, v2
	v_mov_b32_e32 v60, v2
	v_mov_b32_e32 v61, v2
	v_mov_b32_e32 v62, v2
	v_mov_b32_e32 v63, v2
	v_mov_b32_e32 v64, v2
	v_mov_b32_e32 v65, v2
	v_mov_b32_e32 v66, v2
	v_mov_b32_e32 v67, v2
	v_mov_b32_e32 v68, v2
	v_mov_b32_e32 v69, v2
	v_mov_b32_e32 v70, v2
	v_mov_b32_e32 v71, v2
	v_mov_b32_e32 v72, v2
	v_mov_b32_e32 v73, v2
	v_mov_b32_e32 v82, v2
	v_mov_b32_e32 v83, v2
	v_mov_b32_e32 v84, v2
	v_mov_b32_e32 v85, v2
	v_mov_b32_e32 v86, v2
	v_mov_b32_e32 v87, v2
	v_mov_b32_e32 v88, v2
	v_mov_b32_e32 v89, v2
	v_mov_b32_e32 v98, v2
	v_mov_b32_e32 v99, v2
	v_mov_b32_e32 v100, v2
	v_mov_b32_e32 v101, v2
	v_mov_b32_e32 v102, v2
	v_mov_b32_e32 v103, v2
	v_mov_b32_e32 v104, v2
	v_mov_b32_e32 v105, v2
	v_mov_b32_e32 v114, v2
	v_mov_b32_e32 v115, v2
	v_mov_b32_e32 v116, v2
	v_mov_b32_e32 v117, v2
	v_mov_b32_e32 v118, v2
	v_mov_b32_e32 v119, v2
	v_mov_b32_e32 v120, v2
	v_mov_b32_e32 v121, v2
	v_mov_b32_e32 v74, v2
	v_mov_b32_e32 v75, v2
	v_mov_b32_e32 v76, v2
	v_mov_b32_e32 v77, v2
	v_mov_b32_e32 v78, v2
	v_mov_b32_e32 v79, v2
	v_mov_b32_e32 v80, v2
	v_mov_b32_e32 v81, v2
	v_mov_b32_e32 v90, v2
	v_mov_b32_e32 v91, v2
	v_mov_b32_e32 v92, v2
	v_mov_b32_e32 v93, v2
	v_mov_b32_e32 v94, v2
	v_mov_b32_e32 v95, v2
	v_mov_b32_e32 v96, v2
	v_mov_b32_e32 v97, v2
	v_mov_b32_e32 v106, v2
	v_mov_b32_e32 v107, v2
	v_mov_b32_e32 v108, v2
	v_mov_b32_e32 v109, v2
	v_mov_b32_e32 v110, v2
	v_mov_b32_e32 v111, v2
	v_mov_b32_e32 v112, v2
	v_mov_b32_e32 v113, v2
	v_mov_b32_e32 v122, v2
	v_mov_b32_e32 v123, v2
	v_mov_b32_e32 v124, v2
	v_mov_b32_e32 v125, v2
	v_mov_b32_e32 v126, v2
	v_mov_b32_e32 v127, v2
	v_mov_b32_e32 v128, v2
	v_mov_b32_e32 v129, v2
	s_and_b64 vcc, exec, s[12:13]
	s_cbranch_vccnz .Lsp_p11
	s_setprio 1
.Lsp_p11:
.LBB0_1015:
	ds_read_b128 v[146:149], v156
	ds_read_b128 v[150:153], v156 offset:1024
	ds_read_b128 v[160:163], v156 offset:2048
	ds_read_b128 v[164:167], v156 offset:3072
	ds_read_b128 v[168:171], v157
	ds_read_b128 v[172:175], v157 offset:1024
	ds_read_b128 v[176:179], v157 offset:2048
	ds_read_b128 v[180:183], v157 offset:3072
	s_add_u32 s44, s42, 0xfff80080
	s_addc_u32 s45, s43, -1
	s_cmp_eq_u32 s67, 28
	s_cselect_b32 s47, s8, s45
	s_cselect_b32 s46, s9, s44
	s_cselect_b32 s45, s21, s66
	s_cselect_b32 s44, s23, s61
	v_lshl_add_u64 v[216:217], s[42:43], 0, v[138:139]
	s_add_i32 m0, s41, 0xc000
	ds_read_b128 v[184:187], v158
	ds_read_b128 v[188:191], v158 offset:1024
	ds_read_b128 v[192:195], v158 offset:2048
	ds_read_b128 v[196:199], v158 offset:3072
	ds_read_b128 v[200:203], v158 offset:4096
	ds_read_b128 v[204:207], v158 offset:5120
	ds_read_b128 v[208:211], v158 offset:6144
	ds_read_b128 v[212:215], v158 offset:7168
	global_load_lds_dwordx4 v[216:217], off
	v_lshl_add_u64 v[216:217], s[42:43], 0, v[140:141]
	s_add_i32 m0, s41, 0xe000
	s_nop 0
	global_load_lds_dwordx4 v[216:217], off
	s_waitcnt vmcnt(8)
	s_waitcnt lgkmcnt(0)
	s_barrier
	s_waitcnt lgkmcnt(0)
	v_mfma_i32_16x16x64_i8 v[126:129], v[146:149], v[184:187], v[126:129]
	v_mfma_i32_16x16x64_i8 v[122:125], v[160:163], v[184:187], v[122:125]
	v_mfma_i32_16x16x64_i8 v[110:113], v[146:149], v[192:195], v[110:113]
	v_mfma_i32_16x16x64_i8 v[106:109], v[160:163], v[192:195], v[106:109]
	v_mfma_i32_16x16x64_i8 v[94:97], v[146:149], v[200:203], v[94:97]
	v_mfma_i32_16x16x64_i8 v[90:93], v[160:163], v[200:203], v[90:93]
	v_mfma_i32_16x16x64_i8 v[78:81], v[146:149], v[208:211], v[78:81]
	v_mfma_i32_16x16x64_i8 v[74:77], v[160:163], v[208:211], v[74:77]
	v_mfma_i32_16x16x64_i8 v[126:129], v[150:153], v[188:191], v[126:129]
	v_mfma_i32_16x16x64_i8 v[122:125], v[164:167], v[188:191], v[122:125]
	v_mfma_i32_16x16x64_i8 v[110:113], v[150:153], v[196:199], v[110:113]
	v_mfma_i32_16x16x64_i8 v[106:109], v[164:167], v[196:199], v[106:109]
	v_mfma_i32_16x16x64_i8 v[94:97], v[150:153], v[204:207], v[94:97]
	v_mfma_i32_16x16x64_i8 v[90:93], v[164:167], v[204:207], v[90:93]
	v_mfma_i32_16x16x64_i8 v[78:81], v[150:153], v[212:215], v[78:81]
	v_mfma_i32_16x16x64_i8 v[74:77], v[164:167], v[212:215], v[74:77]
	v_mfma_i32_16x16x64_i8 v[118:121], v[168:171], v[184:187], v[118:121]
	v_mfma_i32_16x16x64_i8 v[114:117], v[176:179], v[184:187], v[114:117]
	v_mfma_i32_16x16x64_i8 v[102:105], v[168:171], v[192:195], v[102:105]
	v_mfma_i32_16x16x64_i8 v[98:101], v[176:179], v[192:195], v[98:101]
	v_mfma_i32_16x16x64_i8 v[86:89], v[168:171], v[200:203], v[86:89]
	v_mfma_i32_16x16x64_i8 v[82:85], v[176:179], v[200:203], v[82:85]
	v_mfma_i32_16x16x64_i8 v[70:73], v[168:171], v[208:211], v[70:73]
	v_mfma_i32_16x16x64_i8 v[66:69], v[176:179], v[208:211], v[66:69]
	v_mfma_i32_16x16x64_i8 v[118:121], v[172:175], v[188:191], v[118:121]
	v_mfma_i32_16x16x64_i8 v[114:117], v[180:183], v[188:191], v[114:117]
	v_mfma_i32_16x16x64_i8 v[102:105], v[172:175], v[196:199], v[102:105]
	v_mfma_i32_16x16x64_i8 v[98:101], v[180:183], v[196:199], v[98:101]
	v_mfma_i32_16x16x64_i8 v[86:89], v[172:175], v[204:207], v[86:89]
	v_mfma_i32_16x16x64_i8 v[82:85], v[180:183], v[204:207], v[82:85]
	v_mfma_i32_16x16x64_i8 v[70:73], v[172:175], v[212:215], v[70:73]
	v_mfma_i32_16x16x64_i8 v[66:69], v[180:183], v[212:215], v[66:69]
	s_barrier
	s_add_i32 s68, s56, s19
	v_lshl_add_u64 v[216:217], s[44:45], 0, v[134:135]
	s_mov_b32 m0, s68
	ds_read_b128 v[184:187], v158 offset:16384
	ds_read_b128 v[188:191], v158 offset:17408
	ds_read_b128 v[192:195], v158 offset:18432
	ds_read_b128 v[196:199], v158 offset:19456
	ds_read_b128 v[200:203], v158 offset:20480
	ds_read_b128 v[204:207], v158 offset:21504
	ds_read_b128 v[208:211], v158 offset:22528
	ds_read_b128 v[212:215], v158 offset:23552
	global_load_lds_dwordx4 v[216:217], off
	s_add_i32 m0, s68, 0x2000
	s_add_u32 s68, s44, 0x80000
	v_lshl_add_u64 v[218:219], s[44:45], 0, v[130:131]
	s_addc_u32 s69, s45, 0
	s_add_i32 s72, s57, s19
	global_load_lds_dwordx4 v[218:219], off
	v_lshl_add_u64 v[220:221], s[68:69], 0, v[134:135]
	s_mov_b32 m0, s72
	v_lshl_add_u64 v[222:223], s[46:47], 0, v[132:133]
	global_load_lds_dwordx4 v[220:221], off
	v_lshl_add_u64 v[220:221], s[68:69], 0, v[130:131]
	s_add_i32 m0, s72, 0x2000
	s_nop 0
	global_load_lds_dwordx4 v[220:221], off
	v_lshl_add_u64 v[220:221], s[46:47], 0, v[136:137]
	s_mov_b32 m0, s41
	s_nop 0
	global_load_lds_dwordx4 v[220:221], off
	s_mov_b32 m0, s49
	s_nop 0
	global_load_lds_dwordx4 v[222:223], off
	s_waitcnt vmcnt(8)
	s_waitcnt lgkmcnt(0)
	s_barrier
	s_waitcnt lgkmcnt(0)
	v_mfma_i32_16x16x64_i8 v[62:65], v[146:149], v[184:187], v[62:65]
	v_mfma_i32_16x16x64_i8 v[58:61], v[160:163], v[184:187], v[58:61]
	v_mfma_i32_16x16x64_i8 v[46:49], v[146:149], v[192:195], v[46:49]
	v_mfma_i32_16x16x64_i8 v[42:45], v[160:163], v[192:195], v[42:45]
	v_mfma_i32_16x16x64_i8 v[30:33], v[146:149], v[200:203], v[30:33]
	v_mfma_i32_16x16x64_i8 v[26:29], v[160:163], v[200:203], v[26:29]
	v_mfma_i32_16x16x64_i8 v[14:17], v[146:149], v[208:211], v[14:17]
	v_mfma_i32_16x16x64_i8 v[10:13], v[160:163], v[208:211], v[10:13]
	v_mfma_i32_16x16x64_i8 v[62:65], v[150:153], v[188:191], v[62:65]
	v_mfma_i32_16x16x64_i8 v[58:61], v[164:167], v[188:191], v[58:61]
	v_mfma_i32_16x16x64_i8 v[46:49], v[150:153], v[196:199], v[46:49]
	v_mfma_i32_16x16x64_i8 v[42:45], v[164:167], v[196:199], v[42:45]
	v_mfma_i32_16x16x64_i8 v[30:33], v[150:153], v[204:207], v[30:33]
	v_mfma_i32_16x16x64_i8 v[26:29], v[164:167], v[204:207], v[26:29]
	v_mfma_i32_16x16x64_i8 v[14:17], v[150:153], v[212:215], v[14:17]
	v_mfma_i32_16x16x64_i8 v[10:13], v[164:167], v[212:215], v[10:13]
	v_mfma_i32_16x16x64_i8 v[54:57], v[168:171], v[184:187], v[54:57]
	v_mfma_i32_16x16x64_i8 v[50:53], v[176:179], v[184:187], v[50:53]
	v_mfma_i32_16x16x64_i8 v[38:41], v[168:171], v[192:195], v[38:41]
	v_mfma_i32_16x16x64_i8 v[34:37], v[176:179], v[192:195], v[34:37]
	v_mfma_i32_16x16x64_i8 v[22:25], v[168:171], v[200:203], v[22:25]
	v_mfma_i32_16x16x64_i8 v[18:21], v[176:179], v[200:203], v[18:21]
	v_mfma_i32_16x16x64_i8 v[6:9], v[168:171], v[208:211], v[6:9]
	v_mfma_i32_16x16x64_i8 v[2:5], v[176:179], v[208:211], v[2:5]
	v_mfma_i32_16x16x64_i8 v[54:57], v[172:175], v[188:191], v[54:57]
	v_mfma_i32_16x16x64_i8 v[50:53], v[180:183], v[188:191], v[50:53]
	v_mfma_i32_16x16x64_i8 v[38:41], v[172:175], v[196:199], v[38:41]
	v_mfma_i32_16x16x64_i8 v[34:37], v[180:183], v[196:199], v[34:37]
	v_mfma_i32_16x16x64_i8 v[22:25], v[172:175], v[204:207], v[22:25]
	v_mfma_i32_16x16x64_i8 v[18:21], v[180:183], v[204:207], v[18:21]
	v_mfma_i32_16x16x64_i8 v[6:9], v[172:175], v[212:215], v[6:9]
	v_mfma_i32_16x16x64_i8 v[2:5], v[180:183], v[212:215], v[2:5]
	s_barrier
	s_add_i32 s68, 0, 0x18000
	v_add_u32_e32 v159, s68, v154
	s_add_i32 s69, 0, 0x1c000
	ds_read_b128 v[146:149], v159
	ds_read_b128 v[150:153], v159 offset:1024
	ds_read_b128 v[160:163], v159 offset:2048
	ds_read_b128 v[164:167], v159 offset:3072
	v_add_u32_e32 v159, s69, v154
	ds_read_b128 v[168:171], v159
	ds_read_b128 v[172:175], v159 offset:1024
	ds_read_b128 v[176:179], v159 offset:2048
	ds_read_b128 v[180:183], v159 offset:3072
	s_add_u32 s46, s46, 0x80000
	s_addc_u32 s47, s47, 0
	s_mov_b32 m0, s50
	v_lshl_add_u64 v[224:225], s[46:47], 0, v[136:137]
	ds_read_b128 v[184:187], v158 offset:32768
	ds_read_b128 v[188:191], v158 offset:33792
	ds_read_b128 v[192:195], v158 offset:34816
	ds_read_b128 v[196:199], v158 offset:35840
	ds_read_b128 v[200:203], v158 offset:36864
	ds_read_b128 v[204:207], v158 offset:37888
	ds_read_b128 v[208:211], v158 offset:38912
	ds_read_b128 v[212:215], v158 offset:39936
	global_load_lds_dwordx4 v[224:225], off
	v_lshl_add_u64 v[224:225], s[46:47], 0, v[132:133]
	s_mov_b32 m0, s51
	s_nop 0
	global_load_lds_dwordx4 v[224:225], off
	s_waitcnt vmcnt(8)
	s_waitcnt lgkmcnt(0)
	s_barrier
	s_waitcnt lgkmcnt(0)
	v_mfma_i32_16x16x64_i8 v[126:129], v[146:149], v[184:187], v[126:129]
	v_mfma_i32_16x16x64_i8 v[122:125], v[160:163], v[184:187], v[122:125]
	v_mfma_i32_16x16x64_i8 v[110:113], v[146:149], v[192:195], v[110:113]
	v_mfma_i32_16x16x64_i8 v[106:109], v[160:163], v[192:195], v[106:109]
	v_mfma_i32_16x16x64_i8 v[94:97], v[146:149], v[200:203], v[94:97]
	v_mfma_i32_16x16x64_i8 v[90:93], v[160:163], v[200:203], v[90:93]
	v_mfma_i32_16x16x64_i8 v[78:81], v[146:149], v[208:211], v[78:81]
	v_mfma_i32_16x16x64_i8 v[74:77], v[160:163], v[208:211], v[74:77]
	v_mfma_i32_16x16x64_i8 v[126:129], v[150:153], v[188:191], v[126:129]
	v_mfma_i32_16x16x64_i8 v[122:125], v[164:167], v[188:191], v[122:125]
	v_mfma_i32_16x16x64_i8 v[110:113], v[150:153], v[196:199], v[110:113]
	v_mfma_i32_16x16x64_i8 v[106:109], v[164:167], v[196:199], v[106:109]
	v_mfma_i32_16x16x64_i8 v[94:97], v[150:153], v[204:207], v[94:97]
	v_mfma_i32_16x16x64_i8 v[90:93], v[164:167], v[204:207], v[90:93]
	v_mfma_i32_16x16x64_i8 v[78:81], v[150:153], v[212:215], v[78:81]
	v_mfma_i32_16x16x64_i8 v[74:77], v[164:167], v[212:215], v[74:77]
	v_mfma_i32_16x16x64_i8 v[118:121], v[168:171], v[184:187], v[118:121]
	v_mfma_i32_16x16x64_i8 v[114:117], v[176:179], v[184:187], v[114:117]
	v_mfma_i32_16x16x64_i8 v[102:105], v[168:171], v[192:195], v[102:105]
	v_mfma_i32_16x16x64_i8 v[98:101], v[176:179], v[192:195], v[98:101]
	v_mfma_i32_16x16x64_i8 v[86:89], v[168:171], v[200:203], v[86:89]
	v_mfma_i32_16x16x64_i8 v[82:85], v[176:179], v[200:203], v[82:85]
	v_mfma_i32_16x16x64_i8 v[70:73], v[168:171], v[208:211], v[70:73]
	v_mfma_i32_16x16x64_i8 v[66:69], v[176:179], v[208:211], v[66:69]
	v_mfma_i32_16x16x64_i8 v[118:121], v[172:175], v[188:191], v[118:121]
	v_mfma_i32_16x16x64_i8 v[114:117], v[180:183], v[188:191], v[114:117]
	v_mfma_i32_16x16x64_i8 v[102:105], v[172:175], v[196:199], v[102:105]
	v_mfma_i32_16x16x64_i8 v[98:101], v[180:183], v[196:199], v[98:101]
	v_mfma_i32_16x16x64_i8 v[86:89], v[172:175], v[204:207], v[86:89]
	v_mfma_i32_16x16x64_i8 v[82:85], v[180:183], v[204:207], v[82:85]
	v_mfma_i32_16x16x64_i8 v[70:73], v[172:175], v[212:215], v[70:73]
	v_mfma_i32_16x16x64_i8 v[66:69], v[180:183], v[212:215], v[66:69]
	s_barrier
	s_add_i32 s46, s68, s19
	v_lshl_add_u64 v[216:217], v[216:217], 0, s[4:5]
	s_mov_b32 m0, s46
	ds_read_b128 v[184:187], v158 offset:49152
	ds_read_b128 v[188:191], v158 offset:50176
	ds_read_b128 v[192:195], v158 offset:51200
	ds_read_b128 v[196:199], v158 offset:52224
	ds_read_b128 v[200:203], v158 offset:53248
	ds_read_b128 v[204:207], v158 offset:54272
	ds_read_b128 v[208:211], v158 offset:55296
	ds_read_b128 v[212:215], v158 offset:56320
	global_load_lds_dwordx4 v[216:217], off
	s_add_i32 m0, s46, 0x2000
	s_add_u32 s44, s44, 0x80080
	v_lshl_add_u64 v[216:217], v[218:219], 0, s[4:5]
	s_addc_u32 s45, s45, 0
	s_add_i32 s46, s69, s19
	global_load_lds_dwordx4 v[216:217], off
	v_lshl_add_u64 v[216:217], s[44:45], 0, v[134:135]
	s_mov_b32 m0, s46
	s_nop 0
	global_load_lds_dwordx4 v[216:217], off
	v_lshl_add_u64 v[216:217], s[44:45], 0, v[130:131]
	s_add_i32 m0, s46, 0x2000
	s_nop 0
	global_load_lds_dwordx4 v[216:217], off
	v_lshl_add_u64 v[216:217], v[220:221], 0, s[4:5]
	s_mov_b32 m0, s53
	s_nop 0
	global_load_lds_dwordx4 v[216:217], off
	v_lshl_add_u64 v[216:217], v[222:223], 0, s[4:5]
	s_mov_b32 m0, s54
	s_nop 0
	global_load_lds_dwordx4 v[216:217], off
	s_waitcnt vmcnt(8)
	s_waitcnt lgkmcnt(0)
	s_barrier
	s_waitcnt lgkmcnt(0)
	v_mfma_i32_16x16x64_i8 v[62:65], v[146:149], v[184:187], v[62:65]
	v_mfma_i32_16x16x64_i8 v[58:61], v[160:163], v[184:187], v[58:61]
	v_mfma_i32_16x16x64_i8 v[46:49], v[146:149], v[192:195], v[46:49]
	v_mfma_i32_16x16x64_i8 v[42:45], v[160:163], v[192:195], v[42:45]
	v_mfma_i32_16x16x64_i8 v[30:33], v[146:149], v[200:203], v[30:33]
	v_mfma_i32_16x16x64_i8 v[26:29], v[160:163], v[200:203], v[26:29]
	v_mfma_i32_16x16x64_i8 v[14:17], v[146:149], v[208:211], v[14:17]
	v_mfma_i32_16x16x64_i8 v[10:13], v[160:163], v[208:211], v[10:13]
	v_mfma_i32_16x16x64_i8 v[62:65], v[150:153], v[188:191], v[62:65]
	v_mfma_i32_16x16x64_i8 v[58:61], v[164:167], v[188:191], v[58:61]
	v_mfma_i32_16x16x64_i8 v[46:49], v[150:153], v[196:199], v[46:49]
	v_mfma_i32_16x16x64_i8 v[42:45], v[164:167], v[196:199], v[42:45]
	v_mfma_i32_16x16x64_i8 v[30:33], v[150:153], v[204:207], v[30:33]
	v_mfma_i32_16x16x64_i8 v[26:29], v[164:167], v[204:207], v[26:29]
	v_mfma_i32_16x16x64_i8 v[14:17], v[150:153], v[212:215], v[14:17]
	v_mfma_i32_16x16x64_i8 v[10:13], v[164:167], v[212:215], v[10:13]
	v_mfma_i32_16x16x64_i8 v[54:57], v[168:171], v[184:187], v[54:57]
	v_mfma_i32_16x16x64_i8 v[50:53], v[176:179], v[184:187], v[50:53]
	v_mfma_i32_16x16x64_i8 v[38:41], v[168:171], v[192:195], v[38:41]
	v_mfma_i32_16x16x64_i8 v[34:37], v[176:179], v[192:195], v[34:37]
	v_mfma_i32_16x16x64_i8 v[22:25], v[168:171], v[200:203], v[22:25]
	v_mfma_i32_16x16x64_i8 v[18:21], v[176:179], v[200:203], v[18:21]
	v_mfma_i32_16x16x64_i8 v[6:9], v[168:171], v[208:211], v[6:9]
	v_mfma_i32_16x16x64_i8 v[2:5], v[176:179], v[208:211], v[2:5]
	v_mfma_i32_16x16x64_i8 v[54:57], v[172:175], v[188:191], v[54:57]
	v_mfma_i32_16x16x64_i8 v[50:53], v[180:183], v[188:191], v[50:53]
	v_mfma_i32_16x16x64_i8 v[38:41], v[172:175], v[196:199], v[38:41]
	v_mfma_i32_16x16x64_i8 v[34:37], v[180:183], v[196:199], v[34:37]
	v_mfma_i32_16x16x64_i8 v[22:25], v[172:175], v[204:207], v[22:25]
	v_mfma_i32_16x16x64_i8 v[18:21], v[180:183], v[204:207], v[18:21]
	v_mfma_i32_16x16x64_i8 v[6:9], v[172:175], v[212:215], v[6:9]
	v_mfma_i32_16x16x64_i8 v[2:5], v[180:183], v[212:215], v[2:5]
	s_barrier
	s_add_i32 s67, s67, 2
	s_add_u32 s42, s42, 0x100
	s_addc_u32 s43, s43, 0
	s_add_u32 s61, s61, 0x100
	s_addc_u32 s66, s66, 0
	s_cmp_gt_u32 s67, 29
	s_cbranch_scc0 .LBB0_1015
	s_setprio 0
	s_and_b64 vcc, exec, s[12:13]
	s_cbranch_vccz .LBB0_1018
	s_barrier

.LBB0_1165:
	s_add_u32 s6, s6, 0x158080
	s_addc_u32 s7, s7, 0
	s_add_u32 s8, s26, 0x100
	v_mov_b32_e32 v0, 0
	s_addc_u32 s9, s27, 0
	s_mov_b32 s55, -2
	v_mov_b32_e32 v1, v0
	v_mov_b32_e32 v2, v0
	v_mov_b32_e32 v3, v0
	v_mov_b32_e32 v4, v0
	v_mov_b32_e32 v5, v0
	v_mov_b32_e32 v6, v0
	v_mov_b32_e32 v7, v0
	v_mov_b32_e32 v16, v0
	v_mov_b32_e32 v17, v0
	v_mov_b32_e32 v18, v0
	v_mov_b32_e32 v19, v0
	v_mov_b32_e32 v20, v0
	v_mov_b32_e32 v21, v0
	v_mov_b32_e32 v22, v0
	v_mov_b32_e32 v23, v0
	v_mov_b32_e32 v32, v0
	v_mov_b32_e32 v33, v0
	v_mov_b32_e32 v34, v0
	v_mov_b32_e32 v35, v0
	v_mov_b32_e32 v36, v0
	v_mov_b32_e32 v37, v0
	v_mov_b32_e32 v38, v0
	v_mov_b32_e32 v39, v0
	v_mov_b32_e32 v48, v0
	v_mov_b32_e32 v49, v0
	v_mov_b32_e32 v50, v0
	v_mov_b32_e32 v51, v0
	v_mov_b32_e32 v52, v0
	v_mov_b32_e32 v53, v0
	v_mov_b32_e32 v54, v0
	v_mov_b32_e32 v55, v0
	v_mov_b32_e32 v8, v0
	v_mov_b32_e32 v9, v0
	v_mov_b32_e32 v10, v0
	v_mov_b32_e32 v11, v0
	v_mov_b32_e32 v12, v0
	v_mov_b32_e32 v13, v0
	v_mov_b32_e32 v14, v0
	v_mov_b32_e32 v15, v0
	v_mov_b32_e32 v24, v0
	v_mov_b32_e32 v25, v0
	v_mov_b32_e32 v26, v0
	v_mov_b32_e32 v27, v0
	v_mov_b32_e32 v28, v0
	v_mov_b32_e32 v29, v0
	v_mov_b32_e32 v30, v0
	v_mov_b32_e32 v31, v0
	v_mov_b32_e32 v40, v0
	v_mov_b32_e32 v41, v0
	v_mov_b32_e32 v42, v0
	v_mov_b32_e32 v43, v0
	v_mov_b32_e32 v44, v0
	v_mov_b32_e32 v45, v0
	v_mov_b32_e32 v46, v0
	v_mov_b32_e32 v47, v0
	v_mov_b32_e32 v56, v0
	v_mov_b32_e32 v57, v0
	v_mov_b32_e32 v58, v0
	v_mov_b32_e32 v59, v0
	v_mov_b32_e32 v60, v0
	v_mov_b32_e32 v61, v0
	v_mov_b32_e32 v62, v0
	v_mov_b32_e32 v63, v0
	v_mov_b32_e32 v64, v0
	v_mov_b32_e32 v65, v0
	v_mov_b32_e32 v66, v0
	v_mov_b32_e32 v67, v0
	v_mov_b32_e32 v68, v0
	v_mov_b32_e32 v69, v0
	v_mov_b32_e32 v70, v0
	v_mov_b32_e32 v71, v0
	v_mov_b32_e32 v80, v0
	v_mov_b32_e32 v81, v0
	v_mov_b32_e32 v82, v0
	v_mov_b32_e32 v83, v0
	v_mov_b32_e32 v84, v0
	v_mov_b32_e32 v85, v0
	v_mov_b32_e32 v86, v0
	v_mov_b32_e32 v87, v0
	v_mov_b32_e32 v96, v0
	v_mov_b32_e32 v97, v0
	v_mov_b32_e32 v98, v0
	v_mov_b32_e32 v99, v0
	v_mov_b32_e32 v100, v0
	v_mov_b32_e32 v101, v0
	v_mov_b32_e32 v102, v0
	v_mov_b32_e32 v103, v0
	v_mov_b32_e32 v128, v0
	v_mov_b32_e32 v129, v0
	v_mov_b32_e32 v130, v0
	v_mov_b32_e32 v131, v0
	v_mov_b32_e32 v132, v0
	v_mov_b32_e32 v133, v0
	v_mov_b32_e32 v134, v0
	v_mov_b32_e32 v135, v0
	v_mov_b32_e32 v72, v0
	v_mov_b32_e32 v73, v0
	v_mov_b32_e32 v74, v0
	v_mov_b32_e32 v75, v0
	v_mov_b32_e32 v76, v0
	v_mov_b32_e32 v77, v0
	v_mov_b32_e32 v78, v0
	v_mov_b32_e32 v79, v0
	v_mov_b32_e32 v88, v0
	v_mov_b32_e32 v89, v0
	v_mov_b32_e32 v90, v0
	v_mov_b32_e32 v91, v0
	v_mov_b32_e32 v92, v0
	v_mov_b32_e32 v93, v0
	v_mov_b32_e32 v94, v0
	v_mov_b32_e32 v95, v0
	v_mov_b32_e32 v116, v0
	v_mov_b32_e32 v117, v0
	v_mov_b32_e32 v118, v0
	v_mov_b32_e32 v119, v0
	v_mov_b32_e32 v124, v0
	v_mov_b32_e32 v125, v0
	v_mov_b32_e32 v126, v0
	v_mov_b32_e32 v127, v0
	v_mov_b32_e32 v136, v0
	v_mov_b32_e32 v137, v0
	v_mov_b32_e32 v138, v0
	v_mov_b32_e32 v139, v0
	v_mov_b32_e32 v140, v0
	v_mov_b32_e32 v141, v0
	v_mov_b32_e32 v142, v0
	v_mov_b32_e32 v143, v0
	s_and_b64 vcc, exec, s[18:19]
	s_cbranch_vccnz .Lsp_p13
	s_setprio 1
.Lsp_p13:
.LBB0_1166:
	ds_read_b128 v[104:107], v167
	ds_read_b128 v[108:111], v167 offset:1024
	ds_read_b128 v[112:115], v167 offset:2048
	ds_read_b128 v[120:123], v167 offset:3072
	ds_read_b128 v[158:161], v168
	ds_read_b128 v[170:173], v168 offset:1024
	ds_read_b128 v[174:177], v168 offset:2048
	ds_read_b128 v[178:181], v168 offset:3072
	s_add_u32 s26, s6, 0xffea8080
	s_addc_u32 s27, s7, -1
	s_cmpk_eq_i32 s55, 0x52
	s_cselect_b32 s29, s23, s27
	s_cselect_b32 s28, s22, s26
	s_cselect_b32 s27, s25, s9
	s_cselect_b32 s26, s24, s8
	v_lshl_add_u64 v[214:215], s[6:7], 0, v[152:153]
	s_add_i32 m0, s38, 0xc000
	ds_read_b128 v[182:185], v169
	ds_read_b128 v[186:189], v169 offset:1024
	ds_read_b128 v[190:193], v169 offset:2048
	ds_read_b128 v[194:197], v169 offset:3072
	ds_read_b128 v[198:201], v169 offset:4096
	ds_read_b128 v[202:205], v169 offset:5120
	ds_read_b128 v[206:209], v169 offset:6144
	ds_read_b128 v[210:213], v169 offset:7168
	global_load_lds_dwordx4 v[214:215], off
	v_lshl_add_u64 v[214:215], s[6:7], 0, v[154:155]
	s_add_i32 m0, s38, 0xe000
	s_nop 0
	global_load_lds_dwordx4 v[214:215], off
	s_waitcnt vmcnt(8)
	s_waitcnt lgkmcnt(0)
	s_barrier
	s_waitcnt lgkmcnt(0)
	v_mfma_i32_16x16x64_i8 v[140:143], v[104:107], v[182:185], v[140:143]
	v_mfma_i32_16x16x64_i8 v[136:139], v[112:115], v[182:185], v[136:139]
	v_mfma_i32_16x16x64_i8 v[124:127], v[104:107], v[190:193], v[124:127]
	v_mfma_i32_16x16x64_i8 v[116:119], v[112:115], v[190:193], v[116:119]
	v_mfma_i32_16x16x64_i8 v[92:95], v[104:107], v[198:201], v[92:95]
	v_mfma_i32_16x16x64_i8 v[88:91], v[112:115], v[198:201], v[88:91]
	v_mfma_i32_16x16x64_i8 v[76:79], v[104:107], v[206:209], v[76:79]
	v_mfma_i32_16x16x64_i8 v[72:75], v[112:115], v[206:209], v[72:75]
	v_mfma_i32_16x16x64_i8 v[140:143], v[108:111], v[186:189], v[140:143]
	v_mfma_i32_16x16x64_i8 v[136:139], v[120:123], v[186:189], v[136:139]
	v_mfma_i32_16x16x64_i8 v[124:127], v[108:111], v[194:197], v[124:127]
	v_mfma_i32_16x16x64_i8 v[116:119], v[120:123], v[194:197], v[116:119]
	v_mfma_i32_16x16x64_i8 v[92:95], v[108:111], v[202:205], v[92:95]
	v_mfma_i32_16x16x64_i8 v[88:91], v[120:123], v[202:205], v[88:91]
	v_mfma_i32_16x16x64_i8 v[76:79], v[108:111], v[210:213], v[76:79]
	v_mfma_i32_16x16x64_i8 v[72:75], v[120:123], v[210:213], v[72:75]
	v_mfma_i32_16x16x64_i8 v[132:135], v[158:161], v[182:185], v[132:135]
	v_mfma_i32_16x16x64_i8 v[128:131], v[174:177], v[182:185], v[128:131]
	v_mfma_i32_16x16x64_i8 v[100:103], v[158:161], v[190:193], v[100:103]
	v_mfma_i32_16x16x64_i8 v[96:99], v[174:177], v[190:193], v[96:99]
	v_mfma_i32_16x16x64_i8 v[84:87], v[158:161], v[198:201], v[84:87]
	v_mfma_i32_16x16x64_i8 v[80:83], v[174:177], v[198:201], v[80:83]
	v_mfma_i32_16x16x64_i8 v[68:71], v[158:161], v[206:209], v[68:71]
	v_mfma_i32_16x16x64_i8 v[64:67], v[174:177], v[206:209], v[64:67]
	v_mfma_i32_16x16x64_i8 v[132:135], v[170:173], v[186:189], v[132:135]
	v_mfma_i32_16x16x64_i8 v[128:131], v[178:181], v[186:189], v[128:131]
	v_mfma_i32_16x16x64_i8 v[100:103], v[170:173], v[194:197], v[100:103]
	v_mfma_i32_16x16x64_i8 v[96:99], v[178:181], v[194:197], v[96:99]
	v_mfma_i32_16x16x64_i8 v[84:87], v[170:173], v[202:205], v[84:87]
	v_mfma_i32_16x16x64_i8 v[80:83], v[178:181], v[202:205], v[80:83]
	v_mfma_i32_16x16x64_i8 v[68:71], v[170:173], v[210:213], v[68:71]
	v_mfma_i32_16x16x64_i8 v[64:67], v[178:181], v[210:213], v[64:67]
	s_barrier
	s_add_i32 s56, s48, s35
	v_lshl_add_u64 v[214:215], s[26:27], 0, v[146:147]
	s_mov_b32 m0, s56
	ds_read_b128 v[182:185], v169 offset:16384
	ds_read_b128 v[186:189], v169 offset:17408
	ds_read_b128 v[190:193], v169 offset:18432
	ds_read_b128 v[194:197], v169 offset:19456
	ds_read_b128 v[198:201], v169 offset:20480
	ds_read_b128 v[202:205], v169 offset:21504
	ds_read_b128 v[206:209], v169 offset:22528
	ds_read_b128 v[210:213], v169 offset:23552
	global_load_lds_dwordx4 v[214:215], off
	s_add_i32 m0, s56, 0x2000
	s_add_u32 s56, s26, 0x158000
	v_lshl_add_u64 v[216:217], s[26:27], 0, v[150:151]
	s_addc_u32 s57, s27, 0
	s_add_i32 s58, s49, s35
	global_load_lds_dwordx4 v[216:217], off
	v_lshl_add_u64 v[218:219], s[56:57], 0, v[146:147]
	s_mov_b32 m0, s58
	v_lshl_add_u64 v[220:221], s[28:29], 0, v[148:149]
	global_load_lds_dwordx4 v[218:219], off
	v_lshl_add_u64 v[218:219], s[56:57], 0, v[150:151]
	s_add_i32 m0, s58, 0x2000
	s_nop 0
	global_load_lds_dwordx4 v[218:219], off
	v_lshl_add_u64 v[218:219], s[28:29], 0, v[144:145]
	s_mov_b32 m0, s38
	s_nop 0
	global_load_lds_dwordx4 v[218:219], off
	s_mov_b32 m0, s39
	s_nop 0
	global_load_lds_dwordx4 v[220:221], off
	s_waitcnt vmcnt(8)
	s_waitcnt lgkmcnt(0)
	s_barrier
	s_waitcnt lgkmcnt(0)
	v_mfma_i32_16x16x64_i8 v[60:63], v[104:107], v[182:185], v[60:63]
	v_mfma_i32_16x16x64_i8 v[56:59], v[112:115], v[182:185], v[56:59]
	v_mfma_i32_16x16x64_i8 v[44:47], v[104:107], v[190:193], v[44:47]
	v_mfma_i32_16x16x64_i8 v[40:43], v[112:115], v[190:193], v[40:43]
	v_mfma_i32_16x16x64_i8 v[28:31], v[104:107], v[198:201], v[28:31]
	v_mfma_i32_16x16x64_i8 v[24:27], v[112:115], v[198:201], v[24:27]
	v_mfma_i32_16x16x64_i8 v[12:15], v[104:107], v[206:209], v[12:15]
	v_mfma_i32_16x16x64_i8 v[8:11], v[112:115], v[206:209], v[8:11]
	v_mfma_i32_16x16x64_i8 v[60:63], v[108:111], v[186:189], v[60:63]
	v_mfma_i32_16x16x64_i8 v[56:59], v[120:123], v[186:189], v[56:59]
	v_mfma_i32_16x16x64_i8 v[44:47], v[108:111], v[194:197], v[44:47]
	v_mfma_i32_16x16x64_i8 v[40:43], v[120:123], v[194:197], v[40:43]
	v_mfma_i32_16x16x64_i8 v[28:31], v[108:111], v[202:205], v[28:31]
	v_mfma_i32_16x16x64_i8 v[24:27], v[120:123], v[202:205], v[24:27]
	v_mfma_i32_16x16x64_i8 v[12:15], v[108:111], v[210:213], v[12:15]
	v_mfma_i32_16x16x64_i8 v[8:11], v[120:123], v[210:213], v[8:11]
	v_mfma_i32_16x16x64_i8 v[52:55], v[158:161], v[182:185], v[52:55]
	v_mfma_i32_16x16x64_i8 v[48:51], v[174:177], v[182:185], v[48:51]
	v_mfma_i32_16x16x64_i8 v[36:39], v[158:161], v[190:193], v[36:39]
	v_mfma_i32_16x16x64_i8 v[32:35], v[174:177], v[190:193], v[32:35]
	v_mfma_i32_16x16x64_i8 v[20:23], v[158:161], v[198:201], v[20:23]
	v_mfma_i32_16x16x64_i8 v[16:19], v[174:177], v[198:201], v[16:19]
	v_mfma_i32_16x16x64_i8 v[4:7], v[158:161], v[206:209], v[4:7]
	v_mfma_i32_16x16x64_i8 v[0:3], v[174:177], v[206:209], v[0:3]
	v_mfma_i32_16x16x64_i8 v[52:55], v[170:173], v[186:189], v[52:55]
	v_mfma_i32_16x16x64_i8 v[48:51], v[178:181], v[186:189], v[48:51]
	v_mfma_i32_16x16x64_i8 v[36:39], v[170:173], v[194:197], v[36:39]
	v_mfma_i32_16x16x64_i8 v[32:35], v[178:181], v[194:197], v[32:35]
	v_mfma_i32_16x16x64_i8 v[20:23], v[170:173], v[202:205], v[20:23]
	v_mfma_i32_16x16x64_i8 v[16:19], v[178:181], v[202:205], v[16:19]
	v_mfma_i32_16x16x64_i8 v[4:7], v[170:173], v[210:213], v[4:7]
	v_mfma_i32_16x16x64_i8 v[0:3], v[178:181], v[210:213], v[0:3]
	s_barrier
	s_add_i32 s56, 0, 0x18000
	s_add_i32 s57, 0, 0x1c000
	v_add_u32_e32 v120, s56, v165
	v_add_u32_e32 v162, s57, v165
	ds_read_b128 v[104:107], v120
	ds_read_b128 v[108:111], v120 offset:1024
	ds_read_b128 v[112:115], v120 offset:2048
	ds_read_b128 v[120:123], v120 offset:3072
	ds_read_b128 v[158:161], v162
	ds_read_b128 v[170:173], v162 offset:1024
	ds_read_b128 v[174:177], v162 offset:2048
	ds_read_b128 v[178:181], v162 offset:3072
	s_add_u32 s28, s28, 0x158000
	s_addc_u32 s29, s29, 0
	s_mov_b32 m0, s40
	v_lshl_add_u64 v[222:223], s[28:29], 0, v[144:145]
	ds_read_b128 v[182:185], v169 offset:32768
	ds_read_b128 v[186:189], v169 offset:33792
	ds_read_b128 v[190:193], v169 offset:34816
	ds_read_b128 v[194:197], v169 offset:35840
	ds_read_b128 v[198:201], v169 offset:36864
	ds_read_b128 v[202:205], v169 offset:37888
	ds_read_b128 v[206:209], v169 offset:38912
	ds_read_b128 v[210:213], v169 offset:39936
	global_load_lds_dwordx4 v[222:223], off
	v_lshl_add_u64 v[222:223], s[28:29], 0, v[148:149]
	s_mov_b32 m0, s41
	s_nop 0
	global_load_lds_dwordx4 v[222:223], off
	s_waitcnt vmcnt(8)
	s_waitcnt lgkmcnt(0)
	s_barrier
	s_waitcnt lgkmcnt(0)
	v_mfma_i32_16x16x64_i8 v[140:143], v[104:107], v[182:185], v[140:143]
	v_mfma_i32_16x16x64_i8 v[136:139], v[112:115], v[182:185], v[136:139]
	v_mfma_i32_16x16x64_i8 v[124:127], v[104:107], v[190:193], v[124:127]
	v_mfma_i32_16x16x64_i8 v[116:119], v[112:115], v[190:193], v[116:119]
	v_mfma_i32_16x16x64_i8 v[92:95], v[104:107], v[198:201], v[92:95]
	v_mfma_i32_16x16x64_i8 v[88:91], v[112:115], v[198:201], v[88:91]
	v_mfma_i32_16x16x64_i8 v[76:79], v[104:107], v[206:209], v[76:79]
	v_mfma_i32_16x16x64_i8 v[72:75], v[112:115], v[206:209], v[72:75]
	v_mfma_i32_16x16x64_i8 v[140:143], v[108:111], v[186:189], v[140:143]
	v_mfma_i32_16x16x64_i8 v[136:139], v[120:123], v[186:189], v[136:139]
	v_mfma_i32_16x16x64_i8 v[124:127], v[108:111], v[194:197], v[124:127]
	v_mfma_i32_16x16x64_i8 v[116:119], v[120:123], v[194:197], v[116:119]
	v_mfma_i32_16x16x64_i8 v[92:95], v[108:111], v[202:205], v[92:95]
	v_mfma_i32_16x16x64_i8 v[88:91], v[120:123], v[202:205], v[88:91]
	v_mfma_i32_16x16x64_i8 v[76:79], v[108:111], v[210:213], v[76:79]
	v_mfma_i32_16x16x64_i8 v[72:75], v[120:123], v[210:213], v[72:75]
	v_mfma_i32_16x16x64_i8 v[132:135], v[158:161], v[182:185], v[132:135]
	v_mfma_i32_16x16x64_i8 v[128:131], v[174:177], v[182:185], v[128:131]
	v_mfma_i32_16x16x64_i8 v[100:103], v[158:161], v[190:193], v[100:103]
	v_mfma_i32_16x16x64_i8 v[96:99], v[174:177], v[190:193], v[96:99]
	v_mfma_i32_16x16x64_i8 v[84:87], v[158:161], v[198:201], v[84:87]
	v_mfma_i32_16x16x64_i8 v[80:83], v[174:177], v[198:201], v[80:83]
	v_mfma_i32_16x16x64_i8 v[68:71], v[158:161], v[206:209], v[68:71]
	v_mfma_i32_16x16x64_i8 v[64:67], v[174:177], v[206:209], v[64:67]
	v_mfma_i32_16x16x64_i8 v[132:135], v[170:173], v[186:189], v[132:135]
	v_mfma_i32_16x16x64_i8 v[128:131], v[178:181], v[186:189], v[128:131]
	v_mfma_i32_16x16x64_i8 v[100:103], v[170:173], v[194:197], v[100:103]
	v_mfma_i32_16x16x64_i8 v[96:99], v[178:181], v[194:197], v[96:99]
	v_mfma_i32_16x16x64_i8 v[84:87], v[170:173], v[202:205], v[84:87]
	v_mfma_i32_16x16x64_i8 v[80:83], v[178:181], v[202:205], v[80:83]
	v_mfma_i32_16x16x64_i8 v[68:71], v[170:173], v[210:213], v[68:71]
	v_mfma_i32_16x16x64_i8 v[64:67], v[178:181], v[210:213], v[64:67]
	s_barrier
	s_add_i32 s28, s56, s35
	v_lshl_add_u64 v[214:215], v[214:215], 0, s[16:17]
	s_mov_b32 m0, s28
	ds_read_b128 v[182:185], v169 offset:49152
	ds_read_b128 v[186:189], v169 offset:50176
	ds_read_b128 v[190:193], v169 offset:51200
	ds_read_b128 v[194:197], v169 offset:52224
	ds_read_b128 v[198:201], v169 offset:53248
	ds_read_b128 v[202:205], v169 offset:54272
	ds_read_b128 v[206:209], v169 offset:55296
	ds_read_b128 v[210:213], v169 offset:56320
	global_load_lds_dwordx4 v[214:215], off
	s_add_i32 m0, s28, 0x2000
	s_add_u32 s26, s26, 0x158080
	v_lshl_add_u64 v[214:215], v[216:217], 0, s[16:17]
	s_addc_u32 s27, s27, 0
	s_add_i32 s28, s57, s35
	global_load_lds_dwordx4 v[214:215], off
	v_lshl_add_u64 v[214:215], s[26:27], 0, v[146:147]
	s_mov_b32 m0, s28
	s_nop 0
	global_load_lds_dwordx4 v[214:215], off
	v_lshl_add_u64 v[214:215], s[26:27], 0, v[150:151]
	s_add_i32 m0, s28, 0x2000
	s_nop 0
	global_load_lds_dwordx4 v[214:215], off
	v_lshl_add_u64 v[214:215], v[218:219], 0, s[16:17]
	s_mov_b32 m0, s42
	s_nop 0
	global_load_lds_dwordx4 v[214:215], off
	v_lshl_add_u64 v[214:215], v[220:221], 0, s[16:17]
	s_mov_b32 m0, s43
	s_nop 0
	global_load_lds_dwordx4 v[214:215], off
	s_waitcnt vmcnt(8)
	s_waitcnt lgkmcnt(0)
	s_barrier
	s_waitcnt lgkmcnt(0)
	v_mfma_i32_16x16x64_i8 v[60:63], v[104:107], v[182:185], v[60:63]
	v_mfma_i32_16x16x64_i8 v[56:59], v[112:115], v[182:185], v[56:59]
	v_mfma_i32_16x16x64_i8 v[44:47], v[104:107], v[190:193], v[44:47]
	v_mfma_i32_16x16x64_i8 v[40:43], v[112:115], v[190:193], v[40:43]
	v_mfma_i32_16x16x64_i8 v[28:31], v[104:107], v[198:201], v[28:31]
	v_mfma_i32_16x16x64_i8 v[24:27], v[112:115], v[198:201], v[24:27]
	v_mfma_i32_16x16x64_i8 v[12:15], v[104:107], v[206:209], v[12:15]
	v_mfma_i32_16x16x64_i8 v[8:11], v[112:115], v[206:209], v[8:11]
	v_mfma_i32_16x16x64_i8 v[60:63], v[108:111], v[186:189], v[60:63]
	v_mfma_i32_16x16x64_i8 v[56:59], v[120:123], v[186:189], v[56:59]
	v_mfma_i32_16x16x64_i8 v[44:47], v[108:111], v[194:197], v[44:47]
	v_mfma_i32_16x16x64_i8 v[40:43], v[120:123], v[194:197], v[40:43]
	v_mfma_i32_16x16x64_i8 v[28:31], v[108:111], v[202:205], v[28:31]
	v_mfma_i32_16x16x64_i8 v[24:27], v[120:123], v[202:205], v[24:27]
	v_mfma_i32_16x16x64_i8 v[12:15], v[108:111], v[210:213], v[12:15]
	v_mfma_i32_16x16x64_i8 v[8:11], v[120:123], v[210:213], v[8:11]
	v_mfma_i32_16x16x64_i8 v[52:55], v[158:161], v[182:185], v[52:55]
	v_mfma_i32_16x16x64_i8 v[48:51], v[174:177], v[182:185], v[48:51]
	v_mfma_i32_16x16x64_i8 v[36:39], v[158:161], v[190:193], v[36:39]
	v_mfma_i32_16x16x64_i8 v[32:35], v[174:177], v[190:193], v[32:35]
	v_mfma_i32_16x16x64_i8 v[20:23], v[158:161], v[198:201], v[20:23]
	v_mfma_i32_16x16x64_i8 v[16:19], v[174:177], v[198:201], v[16:19]
	v_mfma_i32_16x16x64_i8 v[4:7], v[158:161], v[206:209], v[4:7]
	v_mfma_i32_16x16x64_i8 v[0:3], v[174:177], v[206:209], v[0:3]
	v_mfma_i32_16x16x64_i8 v[52:55], v[170:173], v[186:189], v[52:55]
	v_mfma_i32_16x16x64_i8 v[48:51], v[178:181], v[186:189], v[48:51]
	v_mfma_i32_16x16x64_i8 v[36:39], v[170:173], v[194:197], v[36:39]
	v_mfma_i32_16x16x64_i8 v[32:35], v[178:181], v[194:197], v[32:35]
	v_mfma_i32_16x16x64_i8 v[20:23], v[170:173], v[202:205], v[20:23]
	v_mfma_i32_16x16x64_i8 v[16:19], v[178:181], v[202:205], v[16:19]
	v_mfma_i32_16x16x64_i8 v[4:7], v[170:173], v[210:213], v[4:7]
	v_mfma_i32_16x16x64_i8 v[0:3], v[178:181], v[210:213], v[0:3]
	s_barrier
	s_add_i32 s55, s55, 2
	s_add_u32 s6, s6, 0x100
	s_addc_u32 s7, s7, 0
	s_add_u32 s8, s8, 0x100
	s_addc_u32 s9, s9, 0
	s_cmpk_gt_u32 s55, 0x53
	s_cbranch_scc0 .LBB0_1166
	s_setprio 0
	s_and_b64 vcc, exec, s[18:19]
	s_cbranch_vccz .LBB0_1169
	s_barrier
